# GDN scan: DMA pieces split over stage and norm waves; A-fragment LDS reads issued two MFMA groups ahead
# speedup vs baseline: 1.0045x; 1.0019x over previous
;     ...
;             const int hn = tid - 384, nt_t = hn >> 1, nt_c0 = 64 * (hn & 1);
;             bf16* MIX = (bf16*)(F.ws + WS_MIX);
;             const bf16* zbase = (const bf16*)(F.ws + WS_GZ) + ((size_t)bh * SEQ + nt_t) * 128 + nt_c0;
;             v4u za[8], zb[8];
; #pragma unroll
;             for (int i = 0; i < 8; ++i) { za[i] = (v4u){0u, 0u, 0u, 0u}; zb[i] = (v4u){0u, 0u, 0u, 0u}; }
.LBB0_971:
	s_or_b64 exec, exec, s[30:31]
	s_waitcnt lgkmcnt(0)
	s_barrier
	s_ashr_i32 s36, s2, 6
	v_and_b32_e32 v146, 63, v101
	s_cmp_gt_i32 s36, 3
	s_mov_b64 s[30:31], -1
	s_cbranch_scc0 .LBB0_986
	s_cmp_gt_u32 s36, 5
	s_cbranch_scc0 .LBB0_980
	v_add_u32_e32 v0, 0xfffffe80, v101
	v_ashrrev_i32_e32 v0, 1, v0
	v_lshlrev_b32_e32 v1, 6, v101
	v_readlane_b32 s30, v254, 44
	v_and_b32_e32 v4, 64, v1
	v_ashrrev_i32_e32 v1, 31, v0
	v_readlane_b32 s31, v254, 45
	s_add_u32 s30, s0, s30
	v_lshlrev_b64 v[2:3], 8, v[0:1]
	s_addc_u32 s31, s1, s31
	v_lshlrev_b32_e32 v96, 1, v4
	v_lshl_add_u64 v[98:99], s[30:31], 0, v[2:3]
	v_lshl_add_u64 v[2:3], v[98:99], 0, v[96:97]
	s_mov_b64 s[30:31], 0x45060000
	v_lshl_add_u64 v[134:135], v[2:3], 0, s[30:31]
	v_readlane_b32 s30, v253, 52
	v_readlane_b32 s31, v253, 53
	s_movk_i32 s2, 0x210
	v_readlane_b32 s38, v255, 9
	v_lshl_add_u64 v[136:137], v[0:1], 0, s[30:31]
	v_mul_lo_u32 v0, v0, s2
	s_add_i32 s2, 0, 0x1c000
	v_readlane_b32 s39, v255, 10
	s_add_u32 s30, s0, s38
	v_lshlrev_b32_e32 v1, 2, v4
	s_addc_u32 s31, s1, s39
	v_add3_u32 v147, s2, v0, v1
	v_lshl_add_u64 v[0:1], s[30:31], 0, v[96:97]
	s_mov_b64 s[30:31], 0x39d80000
	v_lshl_add_u64 v[138:139], v[0:1], 0, s[30:31]
	v_and_b32_e32 v0, 1, v101
	s_add_u32 s30, s0, s38
	v_lshlrev_b32_e32 v140, 7, v0
	s_addc_u32 s31, s1, s39
	v_lshlrev_b64 v[0:1], 12, v[136:137]
	v_mov_b32_e32 v141, v97
	v_lshl_add_u64 v[142:143], s[30:31], 0, v[0:1]
	s_mov_b32 s38, 0
	v_not_b32_e32 v96, 63
	v_mov_b32_e32 v0, 0
	v_mov_b32_e32 v1, 0
	v_mov_b32_e32 v2, 0
	v_mov_b32_e32 v3, 0
	v_mov_b32_e32 v4, 0
	v_mov_b32_e32 v5, 0
	v_mov_b32_e32 v6, 0
	v_mov_b32_e32 v7, 0
	v_mov_b32_e32 v8, 0
	v_mov_b32_e32 v9, 0
	v_mov_b32_e32 v10, 0
	v_mov_b32_e32 v11, 0
	v_mov_b32_e32 v12, 0
	v_mov_b32_e32 v13, 0
	v_mov_b32_e32 v14, 0
	v_mov_b32_e32 v15, 0
	v_mov_b32_e32 v16, 0
	v_mov_b32_e32 v17, 0
	v_mov_b32_e32 v18, 0
	v_mov_b32_e32 v19, 0
	v_mov_b32_e32 v20, 0
	v_mov_b32_e32 v21, 0
	v_mov_b32_e32 v22, 0
	v_mov_b32_e32 v23, 0
	v_mov_b32_e32 v28, 0
	v_mov_b32_e32 v29, 0
	v_mov_b32_e32 v30, 0
	v_mov_b32_e32 v31, 0
	v_mov_b32_e32 v36, 0
	v_mov_b32_e32 v37, 0
	v_mov_b32_e32 v38, 0
	v_mov_b32_e32 v39, 0
	v_readlane_b32 s100, v254, 44
	v_readlane_b32 s101, v254, 45
	v_readlane_b32 s44, v254, 48
	s_add_u32 s100, s0, s100
	s_addc_u32 s101, s1, s101
	s_add_u32 s100, s100, 0x3fe50000
	s_addc_u32 s101, s101, 0
	v_readlane_b32 s41, v254, 44
	s_sub_i32 s46, s81, 0x180
	s_lshl_b32 s46, s46, 5
	s_sub_i32 s44, s44, s41
	s_add_i32 s44, s44, 0x2401000
	v_lshlrev_b32_e32 v160, 4, v146
	v_add_u32_e32 v160, s46, v160
	v_add_u32_e32 v161, s44, v160
	v_add_u32_e32 v160, 0x2000, v160
	s_branch .LBB0_975

; #define GAS __attribute__((address_space(1)))
; #define LAS __attribute__((address_space(3)))
;     ...
;                 const int ch = c2;
;                 const int cz = (ch < 64) ? ch : 63;
; #pragma unroll
;                 for (int i = 0; i < 8; ++i) zb[i] = *(const GAS v4u*)(zbase + (size_t)cz * 64 * 128 + 8 * i);
;                 __builtin_amdgcn_sched_barrier(0);
;                 if (ch > 0 && !(variant & 1)) {
;                     const size_t m = (size_t)b * SEQ + (ch - 1) * 64 + nt_t;
;                     const LAS float* op = (const LAS float*)(L + OT) + nt_t * 132 + nt_c0;
;                     f32x4 x[16]; float ss = 0.f;
; #pragma unroll
;                     for (int q4 = 0; q4 < 16; ++q4) { x[q4] = *(const LAS f32x4*)(op + 4 * q4); ss += (x[q4].x * x[q4].x + x[q4].y * x[q4].y) + (x[q4].z * x[q4].z + x[q4].w * x[q4].w); }
.LBB0_975:
	s_min_u32 s2, s38, 63
	s_lshl_b32 s2, s2, 14
	s_waitcnt vmcnt(0)
	s_cmp_eq_u32 s38, 0
	s_cbranch_scc1 .Lgdn_nd_a
	s_cmp_gt_u32 s38, 62
	s_cbranch_scc1 .Lgdn_nd_a
	s_add_i32 s44, s38, 1
	s_lshl_b32 s40, s44, 14
	s_lshl_b32 s41, s44, 13
	v_add_u32_e32 v162, s40, v160
	v_add_u32_e32 v163, 0x1000, v162
	v_add_u32_e32 v164, 0xc00000, v162
	v_add_u32_e32 v165, 0xc01000, v162
	v_add_u32_e32 v166, 0x1800000, v162
	v_add_u32_e32 v167, 0x1801000, v162
	v_add_u32_e32 v168, s41, v161
	s_add_i32 m0, s46, 0x10000
	s_nop 0
	global_load_lds_dwordx4 v162, s[100:101]
	global_load_lds_dwordx4 v162, s[100:101] offset:1024
	s_add_i32 m0, s46, 0x11000
	s_nop 0
	global_load_lds_dwordx4 v163, s[100:101]
	global_load_lds_dwordx4 v163, s[100:101] offset:1024
	s_add_i32 m0, s46, 0x14000
	s_nop 0
	global_load_lds_dwordx4 v164, s[100:101]
	global_load_lds_dwordx4 v164, s[100:101] offset:1024
	s_add_i32 m0, s46, 0x15000
	s_nop 0
	global_load_lds_dwordx4 v165, s[100:101]
	global_load_lds_dwordx4 v165, s[100:101] offset:1024
	s_add_i32 m0, s46, 0x18000
	s_nop 0
	global_load_lds_dwordx4 v166, s[100:101]
	global_load_lds_dwordx4 v166, s[100:101] offset:1024
	s_add_i32 m0, s46, 0x19000
	s_nop 0
	global_load_lds_dwordx4 v167, s[100:101]
	global_load_lds_dwordx4 v167, s[100:101] offset:1024
	s_add_i32 m0, s46, 0x1b000
	s_nop 0
	global_load_lds_dwordx4 v168, s[100:101]
	global_load_lds_dwordx4 v168, s[100:101] offset:1024
.Lgdn_nd_a:
	v_lshl_add_u64 v[44:45], v[134:135], 0, s[2:3]
	global_load_dwordx4 v[48:51], v[44:45], off offset:48
	global_load_dwordx4 v[52:55], v[44:45], off offset:32
	global_load_dwordx4 v[56:59], v[44:45], off offset:16
	global_load_dwordx4 v[60:63], v[44:45], off
	global_load_dwordx4 v[24:27], v[44:45], off offset:112
	global_load_dwordx4 v[32:35], v[44:45], off offset:96
	global_load_dwordx4 v[40:43], v[44:45], off offset:80
	s_nop 0
	global_load_dwordx4 v[44:47], v[44:45], off offset:64
	s_cmp_eq_u32 s38, 0
	s_cbranch_scc1 .LBB0_977
	ds_read_b128 v[130:133], v147
	ds_read_b128 v[126:129], v147 offset:16
	ds_read_b128 v[76:79], v147 offset:32
	ds_read_b128 v[72:75], v147 offset:48
	ds_read_b128 v[88:91], v147 offset:64
	ds_read_b128 v[122:125], v147 offset:80
	s_waitcnt lgkmcnt(5)
	v_pk_mul_f32 v[64:65], v[132:133], v[132:133]
	v_pk_mul_f32 v[66:67], v[130:131], v[130:131]
	ds_read_b128 v[114:117], v147 offset:112
	v_pk_mov_b32 v[68:69], v[66:67], v[64:65] op_sel:[1,0]
	v_mov_b32_e32 v67, v65
	v_pk_add_f32 v[64:65], v[68:69], v[66:67]
	s_waitcnt lgkmcnt(5)
	v_pk_mul_f32 v[66:67], v[128:129], v[128:129]
	v_pk_mul_f32 v[68:69], v[126:127], v[126:127]
	v_pk_add_f32 v[64:65], v[64:65], v[64:65] op_sel:[0,1] op_sel_hi:[1,0]
	v_pk_mov_b32 v[70:71], v[68:69], v[66:67] op_sel:[1,0]
	v_mov_b32_e32 v69, v67
	v_pk_add_f32 v[66:67], v[70:71], v[68:69]
	s_waitcnt lgkmcnt(3)
	v_mul_f32_e32 v68, v72, v72
	v_mul_f32_e32 v69, v73, v73
	v_pk_add_f32 v[66:67], v[66:67], v[66:67] op_sel:[0,1] op_sel_hi:[1,0]
	v_mov_b32_e32 v65, v68
	v_mov_b32_e32 v67, v69
	v_pk_add_f32 v[64:65], v[64:65], v[66:67]
	v_mul_f32_e32 v66, v77, v77
	v_mul_f32_e32 v68, v79, v79
	v_mul_f32_e32 v70, v74, v74
	v_mul_f32_e32 v71, v75, v75
	v_pk_fma_f32 v[66:67], v[76:77], v[76:77], v[66:67] op_sel_hi:[1,1,0]
	v_pk_fma_f32 v[68:69], v[78:79], v[78:79], v[68:69] op_sel_hi:[1,1,0]
	v_mov_b32_e32 v67, v70
	v_mov_b32_e32 v69, v71
	v_pk_add_f32 v[66:67], v[66:67], v[68:69]
	ds_read_b128 v[68:71], v147 offset:96
	v_pk_add_f32 v[64:65], v[64:65], v[66:67]
	s_waitcnt lgkmcnt(3)
	v_pk_mul_f32 v[66:67], v[90:91], v[90:91]
	v_pk_mul_f32 v[80:81], v[88:89], v[88:89]
	v_pk_add_f32 v[64:65], v[64:65], v[64:65] op_sel:[0,1] op_sel_hi:[1,0]
	v_pk_mov_b32 v[82:83], v[80:81], v[66:67] op_sel:[1,0]
	v_mov_b32_e32 v81, v67
	v_pk_add_f32 v[66:67], v[82:83], v[80:81]
	s_waitcnt lgkmcnt(0)
	v_mul_f32_e32 v80, v68, v68
	v_mul_f32_e32 v81, v69, v69
	v_pk_add_f32 v[66:67], v[66:67], v[66:67] op_sel:[0,1] op_sel_hi:[1,0]
	v_mov_b32_e32 v65, v80
	v_mov_b32_e32 v67, v81
	v_pk_add_f32 v[64:65], v[64:65], v[66:67]
	v_mul_f32_e32 v66, v123, v123
	v_mul_f32_e32 v80, v125, v125
	v_mul_f32_e32 v82, v70, v70
	v_mul_f32_e32 v83, v71, v71
	v_pk_fma_f32 v[66:67], v[122:123], v[122:123], v[66:67] op_sel_hi:[1,1,0]
	v_pk_fma_f32 v[80:81], v[124:125], v[124:125], v[80:81] op_sel_hi:[1,1,0]
	v_mov_b32_e32 v67, v82
	v_mov_b32_e32 v81, v83
	ds_read_b128 v[106:109], v147 offset:128
	ds_read_b128 v[102:105], v147 offset:144
	v_pk_add_f32 v[66:67], v[66:67], v[80:81]
	v_pk_mul_f32 v[80:81], v[114:115], v[114:115]
	v_pk_add_f32 v[64:65], v[64:65], v[66:67]
	v_pk_mul_f32 v[66:67], v[116:117], v[116:117]
	v_pk_add_f32 v[64:65], v[64:65], v[64:65] op_sel:[0,1] op_sel_hi:[1,0]
	v_pk_mov_b32 v[82:83], v[80:81], v[66:67] op_sel:[1,0]
	v_mov_b32_e32 v81, v67
	v_pk_add_f32 v[66:67], v[82:83], v[80:81]
	s_waitcnt lgkmcnt(0)
	v_mul_f32_e32 v80, v102, v102
	v_mul_f32_e32 v81, v103, v103
	v_pk_add_f32 v[66:67], v[66:67], v[66:67] op_sel:[0,1] op_sel_hi:[1,0]
	v_mov_b32_e32 v65, v80
	v_mov_b32_e32 v67, v81
	v_pk_add_f32 v[64:65], v[64:65], v[66:67]
	v_mul_f32_e32 v66, v107, v107
	v_mul_f32_e32 v82, v104, v104
	v_pk_fma_f32 v[66:67], v[106:107], v[106:107], v[66:67] op_sel_hi:[1,1,0]
	v_mul_f32_e32 v80, v109, v109
	v_mul_f32_e32 v86, v105, v105
	v_mov_b32_e32 v67, v82
	v_pk_fma_f32 v[84:85], v[108:109], v[108:109], v[80:81] op_sel_hi:[1,1,0]
	ds_read_b128 v[80:83], v147 offset:160
	ds_read_b128 v[118:121], v147 offset:176
	v_mov_b32_e32 v85, v86
	v_pk_add_f32 v[66:67], v[66:67], v[84:85]
	ds_read_b128 v[110:113], v147 offset:208
	v_pk_add_f32 v[84:85], v[64:65], v[66:67]
	ds_read_b128 v[64:67], v147 offset:192
	s_waitcnt lgkmcnt(3)
	v_pk_mul_f32 v[86:87], v[82:83], v[82:83]
	v_pk_mul_f32 v[92:93], v[80:81], v[80:81]
	v_pk_add_f32 v[84:85], v[84:85], v[84:85] op_sel:[0,1] op_sel_hi:[1,0]
	v_pk_mov_b32 v[94:95], v[92:93], v[86:87] op_sel:[1,0]
	v_mov_b32_e32 v93, v87
	v_pk_add_f32 v[86:87], v[94:95], v[92:93]
	s_waitcnt lgkmcnt(0)
	v_mul_f32_e32 v92, v64, v64
	v_mul_f32_e32 v93, v65, v65
	v_pk_add_f32 v[86:87], v[86:87], v[86:87] op_sel:[0,1] op_sel_hi:[1,0]
	v_mov_b32_e32 v85, v92
	v_mov_b32_e32 v87, v93
	v_pk_add_f32 v[84:85], v[84:85], v[86:87]
	v_mul_f32_e32 v86, v119, v119
	v_mul_f32_e32 v92, v121, v121
	v_mul_f32_e32 v94, v66, v66
	v_mul_f32_e32 v95, v67, v67
	v_pk_fma_f32 v[86:87], v[118:119], v[118:119], v[86:87] op_sel_hi:[1,1,0]
	v_pk_fma_f32 v[92:93], v[120:121], v[120:121], v[92:93] op_sel_hi:[1,1,0]
	v_mov_b32_e32 v87, v94
	v_mov_b32_e32 v93, v95
	v_pk_add_f32 v[86:87], v[86:87], v[92:93]
	v_pk_mul_f32 v[148:149], v[112:113], v[112:113]
	v_pk_add_f32 v[144:145], v[84:85], v[86:87]
	ds_read_b128 v[92:95], v147 offset:224
	ds_read_b128 v[84:87], v147 offset:240
	v_pk_mul_f32 v[150:151], v[110:111], v[110:111]
	v_pk_add_f32 v[144:145], v[144:145], v[144:145] op_sel:[0,1] op_sel_hi:[1,0]
	v_pk_mov_b32 v[152:153], v[150:151], v[148:149] op_sel:[1,0]
	v_mov_b32_e32 v151, v149
	v_pk_add_f32 v[148:149], v[152:153], v[150:151]
	s_waitcnt lgkmcnt(0)
	v_mul_f32_e32 v150, v84, v84
	v_mul_f32_e32 v151, v85, v85
	v_pk_add_f32 v[148:149], v[148:149], v[148:149] op_sel:[0,1] op_sel_hi:[1,0]
	v_mov_b32_e32 v145, v150
	v_mov_b32_e32 v149, v151
	v_pk_add_f32 v[144:145], v[144:145], v[148:149]
	v_mul_f32_e32 v148, v93, v93
	v_mul_f32_e32 v150, v95, v95
	v_mul_f32_e32 v152, v86, v86
	v_mul_f32_e32 v153, v87, v87
	v_pk_fma_f32 v[148:149], v[92:93], v[92:93], v[148:149] op_sel_hi:[1,1,0]
	v_pk_fma_f32 v[150:151], v[94:95], v[94:95], v[150:151] op_sel_hi:[1,1,0]
	v_mov_b32_e32 v149, v152
	v_mov_b32_e32 v151, v153
	v_pk_add_f32 v[148:149], v[148:149], v[150:151]
	v_lshlrev_b32_e32 v150, 16, v36
	v_pk_add_f32 v[144:145], v[144:145], v[148:149]
	v_and_b32_e32 v148, 64, v228
	v_add_f32_e32 v144, v144, v145
	v_xor_b32_e32 v145, 1, v228
	v_add_u32_e32 v148, 64, v148
	v_cmp_lt_i32_e32 vcc, v145, v148
	v_and_b32_e32 v151, 0xffff0000, v36
	s_nop 0
	v_cndmask_b32_e32 v145, v228, v145, vcc
	v_lshlrev_b32_e32 v145, 2, v145
	ds_bpermute_b32 v145, v145, v144
	s_waitcnt lgkmcnt(0)
	v_add_f32_e32 v144, v144, v145
	v_fmamk_f32 v144, v144, 0x3c000000, v226
	v_rsq_f32_e32 v148, v144
	v_lshl_add_u64 v[144:145], v[136:137], 0, v[96:97]
	v_lshlrev_b64 v[144:145], 12, v[144:145]
	v_lshl_add_u64 v[144:145], v[138:139], 0, v[144:145]
	v_pk_mul_f32 v[130:131], v[130:131], v[148:149] op_sel_hi:[1,0]
	v_pk_mul_f32 v[132:133], v[132:133], v[148:149] op_sel_hi:[1,0]
	v_pk_mul_f32 v[130:131], v[130:131], v[150:151]
	v_pk_mul_f32 v[126:127], v[126:127], v[148:149] op_sel_hi:[1,0]
	v_cvt_pk_bf16_f32 v36, v130, v131
	v_lshlrev_b32_e32 v130, 16, v37
	v_and_b32_e32 v131, 0xffff0000, v37
	v_pk_mul_f32 v[130:131], v[132:133], v[130:131]
	v_pk_mul_f32 v[128:129], v[128:129], v[148:149] op_sel_hi:[1,0]
	v_cvt_pk_bf16_f32 v37, v130, v131
	v_lshlrev_b32_e32 v130, 16, v38
	v_and_b32_e32 v131, 0xffff0000, v38
	v_pk_mul_f32 v[126:127], v[126:127], v[130:131]
	v_pk_mul_f32 v[72:73], v[72:73], v[148:149] op_sel_hi:[1,0]
	v_cvt_pk_bf16_f32 v38, v126, v127
	v_lshlrev_b32_e32 v126, 16, v39
	v_and_b32_e32 v127, 0xffff0000, v39
	v_pk_mul_f32 v[126:127], v[128:129], v[126:127]
	v_pk_mul_f32 v[74:75], v[74:75], v[148:149] op_sel_hi:[1,0]
	v_cvt_pk_bf16_f32 v39, v126, v127
	global_store_dwordx4 v[144:145], v[36:39], off offset:2560
	s_nop 1
	v_pk_mul_f32 v[38:39], v[76:77], v[148:149] op_sel_hi:[1,0]
	v_lshlrev_b32_e32 v76, 16, v28
	v_and_b32_e32 v77, 0xffff0000, v28
	v_pk_mul_f32 v[38:39], v[38:39], v[76:77]
	v_pk_mul_f32 v[36:37], v[78:79], v[148:149] op_sel_hi:[1,0]
	v_cvt_pk_bf16_f32 v28, v38, v39
	v_lshlrev_b32_e32 v38, 16, v29
	v_and_b32_e32 v39, 0xffff0000, v29
	v_pk_mul_f32 v[36:37], v[36:37], v[38:39]
	v_pk_mul_f32 v[38:39], v[122:123], v[148:149] op_sel_hi:[1,0]
	v_cvt_pk_bf16_f32 v29, v36, v37
	v_lshlrev_b32_e32 v36, 16, v30
	v_and_b32_e32 v37, 0xffff0000, v30
	v_pk_mul_f32 v[36:37], v[72:73], v[36:37]
	v_lshlrev_b32_e32 v72, 16, v20
	v_cvt_pk_bf16_f32 v30, v36, v37
	v_lshlrev_b32_e32 v36, 16, v31
	v_and_b32_e32 v37, 0xffff0000, v31
	v_pk_mul_f32 v[36:37], v[74:75], v[36:37]
	v_and_b32_e32 v73, 0xffff0000, v20
	v_cvt_pk_bf16_f32 v31, v36, v37
	global_store_dwordx4 v[144:145], v[28:31], off offset:2576
	v_pk_mul_f32 v[36:37], v[124:125], v[148:149] op_sel_hi:[1,0]
	s_nop 0
	v_pk_mul_f32 v[30:31], v[88:89], v[148:149] op_sel_hi:[1,0]
	v_pk_mul_f32 v[28:29], v[90:91], v[148:149] op_sel_hi:[1,0]
	v_pk_mul_f32 v[30:31], v[30:31], v[72:73]
	s_nop 0
	v_cvt_pk_bf16_f32 v20, v30, v31
	v_lshlrev_b32_e32 v30, 16, v21
	v_and_b32_e32 v31, 0xffff0000, v21
	v_pk_mul_f32 v[28:29], v[28:29], v[30:31]
	v_pk_mul_f32 v[30:31], v[114:115], v[148:149] op_sel_hi:[1,0]
	v_cvt_pk_bf16_f32 v21, v28, v29
	v_lshlrev_b32_e32 v28, 16, v22
	v_and_b32_e32 v29, 0xffff0000, v22
	v_pk_mul_f32 v[28:29], v[38:39], v[28:29]
	s_nop 0
	v_cvt_pk_bf16_f32 v22, v28, v29
	v_lshlrev_b32_e32 v28, 16, v23
	v_and_b32_e32 v29, 0xffff0000, v23
	v_pk_mul_f32 v[28:29], v[36:37], v[28:29]
	v_lshlrev_b32_e32 v36, 16, v16
	v_cvt_pk_bf16_f32 v23, v28, v29
	global_store_dwordx4 v[144:145], v[20:23], off offset:2592
	v_and_b32_e32 v37, 0xffff0000, v16
	v_pk_mul_f32 v[28:29], v[116:117], v[148:149] op_sel_hi:[1,0]
	v_pk_mul_f32 v[22:23], v[68:69], v[148:149] op_sel_hi:[1,0]
	v_pk_mul_f32 v[20:21], v[70:71], v[148:149] op_sel_hi:[1,0]
	v_pk_mul_f32 v[22:23], v[22:23], v[36:37]
	s_nop 0
	v_cvt_pk_bf16_f32 v16, v22, v23
	v_lshlrev_b32_e32 v22, 16, v17
	v_and_b32_e32 v23, 0xffff0000, v17
	v_pk_mul_f32 v[20:21], v[20:21], v[22:23]
	v_pk_mul_f32 v[22:23], v[102:103], v[148:149] op_sel_hi:[1,0]
	v_cvt_pk_bf16_f32 v17, v20, v21
	v_lshlrev_b32_e32 v20, 16, v18
	v_and_b32_e32 v21, 0xffff0000, v18
	v_pk_mul_f32 v[20:21], v[30:31], v[20:21]
	s_nop 0
	v_cvt_pk_bf16_f32 v18, v20, v21
	v_lshlrev_b32_e32 v20, 16, v19
	v_and_b32_e32 v21, 0xffff0000, v19
	v_pk_mul_f32 v[20:21], v[28:29], v[20:21]
	v_lshlrev_b32_e32 v28, 16, v12
	v_cvt_pk_bf16_f32 v19, v20, v21
	global_store_dwordx4 v[144:145], v[16:19], off offset:2608
	v_and_b32_e32 v29, 0xffff0000, v12
	v_pk_mul_f32 v[20:21], v[104:105], v[148:149] op_sel_hi:[1,0]
	v_pk_mul_f32 v[18:19], v[106:107], v[148:149] op_sel_hi:[1,0]
	v_pk_mul_f32 v[16:17], v[108:109], v[148:149] op_sel_hi:[1,0]
	v_pk_mul_f32 v[18:19], v[18:19], v[28:29]
	s_nop 0
	v_cvt_pk_bf16_f32 v12, v18, v19
	v_lshlrev_b32_e32 v18, 16, v13
	v_and_b32_e32 v19, 0xffff0000, v13
	v_pk_mul_f32 v[16:17], v[16:17], v[18:19]
	v_pk_mul_f32 v[18:19], v[118:119], v[148:149] op_sel_hi:[1,0]
	v_cvt_pk_bf16_f32 v13, v16, v17
	v_lshlrev_b32_e32 v16, 16, v14
	v_and_b32_e32 v17, 0xffff0000, v14
	v_pk_mul_f32 v[16:17], v[22:23], v[16:17]
	s_nop 0
	v_cvt_pk_bf16_f32 v14, v16, v17
	v_lshlrev_b32_e32 v16, 16, v15
	v_and_b32_e32 v17, 0xffff0000, v15
	v_pk_mul_f32 v[16:17], v[20:21], v[16:17]
	v_lshlrev_b32_e32 v20, 16, v8
	v_cvt_pk_bf16_f32 v15, v16, v17
	global_store_dwordx4 v[144:145], v[12:15], off offset:2624
	v_and_b32_e32 v21, 0xffff0000, v8
	v_pk_mul_f32 v[16:17], v[120:121], v[148:149] op_sel_hi:[1,0]
	v_pk_mul_f32 v[14:15], v[80:81], v[148:149] op_sel_hi:[1,0]
	v_pk_mul_f32 v[12:13], v[82:83], v[148:149] op_sel_hi:[1,0]
	v_pk_mul_f32 v[14:15], v[14:15], v[20:21]
	s_nop 0
	v_cvt_pk_bf16_f32 v8, v14, v15
	v_lshlrev_b32_e32 v14, 16, v9
	v_and_b32_e32 v15, 0xffff0000, v9
	v_pk_mul_f32 v[12:13], v[12:13], v[14:15]
	v_pk_mul_f32 v[14:15], v[110:111], v[148:149] op_sel_hi:[1,0]
	v_cvt_pk_bf16_f32 v9, v12, v13
	v_lshlrev_b32_e32 v12, 16, v10
	v_and_b32_e32 v13, 0xffff0000, v10
	v_pk_mul_f32 v[12:13], v[18:19], v[12:13]
	s_nop 0
	v_cvt_pk_bf16_f32 v10, v12, v13
	v_lshlrev_b32_e32 v12, 16, v11
	v_and_b32_e32 v13, 0xffff0000, v11
	v_pk_mul_f32 v[12:13], v[16:17], v[12:13]
	v_lshlrev_b32_e32 v16, 16, v4
	v_cvt_pk_bf16_f32 v11, v12, v13
	global_store_dwordx4 v[144:145], v[8:11], off offset:2640
	v_and_b32_e32 v17, 0xffff0000, v4
	v_pk_mul_f32 v[12:13], v[112:113], v[148:149] op_sel_hi:[1,0]
	v_pk_mul_f32 v[10:11], v[64:65], v[148:149] op_sel_hi:[1,0]
	v_pk_mul_f32 v[8:9], v[66:67], v[148:149] op_sel_hi:[1,0]
	v_pk_mul_f32 v[10:11], v[10:11], v[16:17]
	s_nop 0
	v_cvt_pk_bf16_f32 v4, v10, v11
	v_lshlrev_b32_e32 v10, 16, v5
	v_and_b32_e32 v11, 0xffff0000, v5
	v_pk_mul_f32 v[8:9], v[8:9], v[10:11]
	v_pk_mul_f32 v[10:11], v[84:85], v[148:149] op_sel_hi:[1,0]
	v_cvt_pk_bf16_f32 v5, v8, v9
	v_lshlrev_b32_e32 v8, 16, v6
	v_and_b32_e32 v9, 0xffff0000, v6
	v_pk_mul_f32 v[8:9], v[14:15], v[8:9]
	s_nop 0
	v_cvt_pk_bf16_f32 v6, v8, v9
	v_lshlrev_b32_e32 v8, 16, v7
	v_and_b32_e32 v9, 0xffff0000, v7
	v_pk_mul_f32 v[8:9], v[12:13], v[8:9]
	v_lshlrev_b32_e32 v12, 16, v0
	v_cvt_pk_bf16_f32 v7, v8, v9
	global_store_dwordx4 v[144:145], v[4:7], off offset:2656
	v_and_b32_e32 v13, 0xffff0000, v0
	v_pk_mul_f32 v[8:9], v[86:87], v[148:149] op_sel_hi:[1,0]
	v_pk_mul_f32 v[6:7], v[92:93], v[148:149] op_sel_hi:[1,0]
	v_pk_mul_f32 v[4:5], v[94:95], v[148:149] op_sel_hi:[1,0]
	v_pk_mul_f32 v[6:7], v[6:7], v[12:13]
	s_nop 0
	v_cvt_pk_bf16_f32 v0, v6, v7
	v_lshlrev_b32_e32 v6, 16, v1
	v_and_b32_e32 v7, 0xffff0000, v1
	v_pk_mul_f32 v[4:5], v[4:5], v[6:7]
	s_nop 0
	v_cvt_pk_bf16_f32 v1, v4, v5
	v_lshlrev_b32_e32 v4, 16, v2
	v_and_b32_e32 v5, 0xffff0000, v2
	v_pk_mul_f32 v[4:5], v[10:11], v[4:5]
	s_nop 0
	v_cvt_pk_bf16_f32 v2, v4, v5
	v_lshlrev_b32_e32 v4, 16, v3
	v_and_b32_e32 v5, 0xffff0000, v3
	v_pk_mul_f32 v[4:5], v[8:9], v[4:5]
	s_nop 0
	v_cvt_pk_bf16_f32 v3, v4, v5
	global_store_dwordx4 v[144:145], v[0:3], off offset:2672
.LBB0_977:
	s_waitcnt lgkmcnt(0)
	s_barrier
	s_waitcnt vmcnt(16)
	s_waitcnt lgkmcnt(0)
	s_barrier
	s_mov_b64 s[30:31], -1
	s_cmp_gt_u32 s38, 63
	v_readfirstlane_b32 s2, v0
	s_cbranch_scc1 .LBB0_974
	s_add_i32 s44, s38, 2
	s_lshl_b32 s40, s44, 14
	s_lshl_b32 s41, s44, 13
	v_add_u32_e32 v162, s40, v160
	v_add_u32_e32 v163, 0x1000, v162
	v_add_u32_e32 v164, 0xc00000, v162
	v_add_u32_e32 v165, 0xc01000, v162
	v_add_u32_e32 v166, 0x1800000, v162
	v_add_u32_e32 v167, 0x1801000, v162
	v_add_u32_e32 v168, s41, v161
	s_add_i32 m0, s46, 0x2000
	s_nop 0
	global_load_lds_dwordx4 v162, s[100:101]
	global_load_lds_dwordx4 v162, s[100:101] offset:1024
	s_add_i32 m0, s46, 0x3000
	s_nop 0
	global_load_lds_dwordx4 v163, s[100:101]
	global_load_lds_dwordx4 v163, s[100:101] offset:1024
	s_add_i32 m0, s46, 0x6000
	s_nop 0
	global_load_lds_dwordx4 v164, s[100:101]
	global_load_lds_dwordx4 v164, s[100:101] offset:1024
	s_add_i32 m0, s46, 0x7000
	s_nop 0
	global_load_lds_dwordx4 v165, s[100:101]
	global_load_lds_dwordx4 v165, s[100:101] offset:1024
	s_add_i32 m0, s46, 0xa000
	s_nop 0
	global_load_lds_dwordx4 v166, s[100:101]
	global_load_lds_dwordx4 v166, s[100:101] offset:1024
	s_add_i32 m0, s46, 0xb000
	s_nop 0
	global_load_lds_dwordx4 v167, s[100:101]
	global_load_lds_dwordx4 v167, s[100:101] offset:1024
	s_add_i32 m0, s46, 0xd000
	s_nop 0
	global_load_lds_dwordx4 v168, s[100:101]
	global_load_lds_dwordx4 v168, s[100:101] offset:1024
.Lgdn_nd_b:
	v_lshl_add_u64 v[0:1], v[98:99], 0, v[140:141]
	s_mov_b64 s[30:31], 0x45064000
	s_mov_b32 s2, 0x45064000
	v_lshl_add_u64 v[2:3], v[0:1], 0, s[30:31]
	v_add_co_u32_e32 v8, vcc, s2, v0
	s_mov_b64 s[30:31], 0x45064040
	s_nop 0
	v_addc_co_u32_e32 v9, vcc, 0, v1, vcc
	v_lshl_add_u64 v[10:11], v[0:1], 0, s[30:31]
	global_load_dwordx4 v[36:39], v[8:9], off
	global_load_dwordx4 v[16:19], v[2:3], off offset:48
	global_load_dwordx4 v[20:23], v[2:3], off offset:32
	global_load_dwordx4 v[28:31], v[2:3], off offset:16
	s_nop 0
	global_load_dwordx4 v[0:3], v[10:11], off offset:48
	global_load_dwordx4 v[4:7], v[10:11], off offset:32
	global_load_dwordx4 v[12:15], v[8:9], off offset:64
	s_nop 0
	global_load_dwordx4 v[8:11], v[10:11], off offset:16
	ds_read_b128 v[130:133], v147
	ds_read_b128 v[126:129], v147 offset:16
	ds_read_b128 v[76:79], v147 offset:32
	ds_read_b128 v[72:75], v147 offset:48
	ds_read_b128 v[88:91], v147 offset:64
	ds_read_b128 v[122:125], v147 offset:80
	s_waitcnt lgkmcnt(5)
	v_pk_mul_f32 v[64:65], v[132:133], v[132:133]
	v_pk_mul_f32 v[66:67], v[130:131], v[130:131]
	s_mov_b64 s[30:31], 0x8000
	v_pk_mov_b32 v[68:69], v[66:67], v[64:65] op_sel:[1,0]
	v_mov_b32_e32 v67, v65
	v_pk_add_f32 v[64:65], v[68:69], v[66:67]
	s_waitcnt lgkmcnt(4)
	v_pk_mul_f32 v[66:67], v[128:129], v[128:129]
	v_pk_mul_f32 v[68:69], v[126:127], v[126:127]
	v_pk_add_f32 v[64:65], v[64:65], v[64:65] op_sel:[0,1] op_sel_hi:[1,0]
	v_pk_mov_b32 v[70:71], v[68:69], v[66:67] op_sel:[1,0]
	v_mov_b32_e32 v69, v67
	v_pk_add_f32 v[66:67], v[70:71], v[68:69]
	s_waitcnt lgkmcnt(2)
	v_mul_f32_e32 v68, v72, v72
	v_mul_f32_e32 v69, v73, v73
	v_pk_add_f32 v[66:67], v[66:67], v[66:67] op_sel:[0,1] op_sel_hi:[1,0]
	v_mov_b32_e32 v65, v68
	v_mov_b32_e32 v67, v69
	v_pk_add_f32 v[64:65], v[64:65], v[66:67]
	v_mul_f32_e32 v66, v77, v77
	v_mul_f32_e32 v68, v79, v79
	v_mul_f32_e32 v70, v74, v74
	v_mul_f32_e32 v71, v75, v75
	v_pk_fma_f32 v[66:67], v[76:77], v[76:77], v[66:67] op_sel_hi:[1,1,0]
	v_pk_fma_f32 v[68:69], v[78:79], v[78:79], v[68:69] op_sel_hi:[1,1,0]
	v_mov_b32_e32 v67, v70
	v_mov_b32_e32 v69, v71
	v_pk_add_f32 v[66:67], v[66:67], v[68:69]
	ds_read_b128 v[68:71], v147 offset:96
	ds_read_b128 v[114:117], v147 offset:112
	v_pk_add_f32 v[64:65], v[64:65], v[66:67]
	s_waitcnt lgkmcnt(3)
	v_pk_mul_f32 v[66:67], v[90:91], v[90:91]
	v_pk_mul_f32 v[80:81], v[88:89], v[88:89]
	v_pk_add_f32 v[64:65], v[64:65], v[64:65] op_sel:[0,1] op_sel_hi:[1,0]
	v_pk_mov_b32 v[82:83], v[80:81], v[66:67] op_sel:[1,0]
	v_mov_b32_e32 v81, v67
	v_pk_add_f32 v[66:67], v[82:83], v[80:81]
	s_waitcnt lgkmcnt(1)
	v_mul_f32_e32 v80, v68, v68
	v_mul_f32_e32 v81, v69, v69
	v_pk_add_f32 v[66:67], v[66:67], v[66:67] op_sel:[0,1] op_sel_hi:[1,0]
	v_mov_b32_e32 v65, v80
	v_mov_b32_e32 v67, v81
	v_pk_add_f32 v[64:65], v[64:65], v[66:67]
	v_mul_f32_e32 v66, v123, v123
	v_mul_f32_e32 v80, v125, v125
	v_mul_f32_e32 v82, v70, v70
	v_mul_f32_e32 v83, v71, v71
	v_pk_fma_f32 v[66:67], v[122:123], v[122:123], v[66:67] op_sel_hi:[1,1,0]
	v_pk_fma_f32 v[80:81], v[124:125], v[124:125], v[80:81] op_sel_hi:[1,1,0]
	v_mov_b32_e32 v67, v82
	v_mov_b32_e32 v81, v83
	ds_read_b128 v[106:109], v147 offset:128
	ds_read_b128 v[102:105], v147 offset:144
	v_pk_add_f32 v[66:67], v[66:67], v[80:81]
	s_waitcnt lgkmcnt(2)
	v_pk_mul_f32 v[80:81], v[114:115], v[114:115]
	v_pk_add_f32 v[64:65], v[64:65], v[66:67]
	v_pk_mul_f32 v[66:67], v[116:117], v[116:117]
	v_pk_add_f32 v[64:65], v[64:65], v[64:65] op_sel:[0,1] op_sel_hi:[1,0]
	v_pk_mov_b32 v[82:83], v[80:81], v[66:67] op_sel:[1,0]
	v_mov_b32_e32 v81, v67
	v_pk_add_f32 v[66:67], v[82:83], v[80:81]
	s_waitcnt lgkmcnt(0)
	v_mul_f32_e32 v80, v102, v102
	v_mul_f32_e32 v81, v103, v103
	v_pk_add_f32 v[66:67], v[66:67], v[66:67] op_sel:[0,1] op_sel_hi:[1,0]
	v_mov_b32_e32 v65, v80
	v_mov_b32_e32 v67, v81
	v_pk_add_f32 v[64:65], v[64:65], v[66:67]
	v_mul_f32_e32 v66, v107, v107
	v_mul_f32_e32 v82, v104, v104
	v_pk_fma_f32 v[66:67], v[106:107], v[106:107], v[66:67] op_sel_hi:[1,1,0]
	v_mul_f32_e32 v80, v109, v109
	v_mul_f32_e32 v86, v105, v105
	v_mov_b32_e32 v67, v82
	v_pk_fma_f32 v[84:85], v[108:109], v[108:109], v[80:81] op_sel_hi:[1,1,0]
	ds_read_b128 v[80:83], v147 offset:160
	ds_read_b128 v[118:121], v147 offset:176
	v_mov_b32_e32 v85, v86
	v_pk_add_f32 v[66:67], v[66:67], v[84:85]
	ds_read_b128 v[110:113], v147 offset:208
	v_pk_add_f32 v[84:85], v[64:65], v[66:67]
	ds_read_b128 v[64:67], v147 offset:192
	s_waitcnt lgkmcnt(3)
	v_pk_mul_f32 v[86:87], v[82:83], v[82:83]
	v_pk_mul_f32 v[92:93], v[80:81], v[80:81]
	v_pk_add_f32 v[84:85], v[84:85], v[84:85] op_sel:[0,1] op_sel_hi:[1,0]
	v_pk_mov_b32 v[94:95], v[92:93], v[86:87] op_sel:[1,0]
	v_mov_b32_e32 v93, v87
	v_pk_add_f32 v[86:87], v[94:95], v[92:93]
	s_waitcnt lgkmcnt(0)
	v_mul_f32_e32 v92, v64, v64
	v_mul_f32_e32 v93, v65, v65
	v_pk_add_f32 v[86:87], v[86:87], v[86:87] op_sel:[0,1] op_sel_hi:[1,0]
	v_mov_b32_e32 v85, v92
	v_mov_b32_e32 v87, v93
	v_pk_add_f32 v[84:85], v[84:85], v[86:87]
	v_mul_f32_e32 v86, v119, v119
	v_mul_f32_e32 v92, v121, v121
	v_mul_f32_e32 v94, v66, v66
	v_mul_f32_e32 v95, v67, v67
	v_pk_fma_f32 v[86:87], v[118:119], v[118:119], v[86:87] op_sel_hi:[1,1,0]
	v_pk_fma_f32 v[92:93], v[120:121], v[120:121], v[92:93] op_sel_hi:[1,1,0]
	v_mov_b32_e32 v87, v94
	v_mov_b32_e32 v93, v95
	v_pk_add_f32 v[86:87], v[86:87], v[92:93]
	v_pk_mul_f32 v[148:149], v[112:113], v[112:113]
	v_pk_add_f32 v[144:145], v[84:85], v[86:87]
	ds_read_b128 v[92:95], v147 offset:224
	ds_read_b128 v[84:87], v147 offset:240
	v_pk_mul_f32 v[150:151], v[110:111], v[110:111]
	v_pk_add_f32 v[144:145], v[144:145], v[144:145] op_sel:[0,1] op_sel_hi:[1,0]
	v_pk_mov_b32 v[152:153], v[150:151], v[148:149] op_sel:[1,0]
	v_mov_b32_e32 v151, v149
	v_pk_add_f32 v[148:149], v[152:153], v[150:151]
	s_waitcnt lgkmcnt(0)
	v_mul_f32_e32 v150, v84, v84
	v_mul_f32_e32 v151, v85, v85
	v_pk_add_f32 v[148:149], v[148:149], v[148:149] op_sel:[0,1] op_sel_hi:[1,0]
	v_mov_b32_e32 v145, v150
	v_mov_b32_e32 v149, v151
	v_pk_add_f32 v[144:145], v[144:145], v[148:149]
	v_mul_f32_e32 v148, v93, v93
	v_mul_f32_e32 v150, v95, v95
	v_mul_f32_e32 v152, v86, v86
	v_mul_f32_e32 v153, v87, v87
	v_pk_fma_f32 v[148:149], v[92:93], v[92:93], v[148:149] op_sel_hi:[1,1,0]
	v_pk_fma_f32 v[150:151], v[94:95], v[94:95], v[150:151] op_sel_hi:[1,1,0]
	v_mov_b32_e32 v149, v152
	v_mov_b32_e32 v151, v153
	v_pk_add_f32 v[148:149], v[148:149], v[150:151]
	s_waitcnt vmcnt(26)
	v_lshlrev_b32_e32 v150, 16, v60
	v_pk_add_f32 v[144:145], v[144:145], v[148:149]
	v_and_b32_e32 v148, 64, v228
	v_add_f32_e32 v144, v144, v145
	v_xor_b32_e32 v145, 1, v228
	v_add_u32_e32 v148, 64, v148
	v_cmp_lt_i32_e32 vcc, v145, v148
	v_and_b32_e32 v151, 0xffff0000, v60
	v_lshl_add_u64 v[148:149], v[142:143], 0, v[140:141]
	v_cndmask_b32_e32 v145, v228, v145, vcc
	v_lshlrev_b32_e32 v145, 2, v145
	ds_bpermute_b32 v145, v145, v144
	v_lshl_add_u64 v[98:99], v[98:99], 0, s[30:31]
	s_mov_b64 s[30:31], 0x80000
	s_add_i32 s2, s38, 2
	v_lshl_add_u64 v[142:143], v[142:143], 0, s[30:31]
	s_waitcnt lgkmcnt(0)
	v_add_f32_e32 v144, v144, v145
	v_fmamk_f32 v144, v144, 0x3c000000, v226
	v_rsq_f32_e32 v144, v144
	v_add_u32_e32 v96, 0x80, v96
	s_mov_b64 s[30:31], 0
	v_pk_mul_f32 v[130:131], v[130:131], v[144:145] op_sel_hi:[1,0]
	s_nop 0
	v_pk_mul_f32 v[130:131], v[130:131], v[150:151]
	v_pk_mul_f32 v[132:133], v[132:133], v[144:145] op_sel_hi:[1,0]
	v_cvt_pk_bf16_f32 v60, v130, v131
	v_lshlrev_b32_e32 v130, 16, v61
	v_and_b32_e32 v131, 0xffff0000, v61
	v_pk_mul_f32 v[130:131], v[132:133], v[130:131]
	v_pk_mul_f32 v[126:127], v[126:127], v[144:145] op_sel_hi:[1,0]
	v_cvt_pk_bf16_f32 v61, v130, v131
	v_lshlrev_b32_e32 v130, 16, v62
	v_and_b32_e32 v131, 0xffff0000, v62
	v_pk_mul_f32 v[126:127], v[126:127], v[130:131]
	v_pk_mul_f32 v[128:129], v[128:129], v[144:145] op_sel_hi:[1,0]
	v_cvt_pk_bf16_f32 v62, v126, v127
	v_lshlrev_b32_e32 v126, 16, v63
	v_and_b32_e32 v127, 0xffff0000, v63
	v_pk_mul_f32 v[126:127], v[128:129], v[126:127]
	v_pk_mul_f32 v[72:73], v[72:73], v[144:145] op_sel_hi:[1,0]
	v_cvt_pk_bf16_f32 v63, v126, v127
	v_add_co_u32_e32 v126, vcc, s63, v148
	v_pk_mul_f32 v[74:75], v[74:75], v[144:145] op_sel_hi:[1,0]
	s_nop 0
	v_addc_co_u32_e32 v127, vcc, 0, v149, vcc
	global_store_dwordx4 v[126:127], v[60:63], off offset:2560
	s_nop 1
	v_pk_mul_f32 v[62:63], v[76:77], v[144:145] op_sel_hi:[1,0]
	v_lshlrev_b32_e32 v76, 16, v56
	v_and_b32_e32 v77, 0xffff0000, v56
	v_pk_mul_f32 v[62:63], v[62:63], v[76:77]
	v_pk_mul_f32 v[60:61], v[78:79], v[144:145] op_sel_hi:[1,0]
	v_cvt_pk_bf16_f32 v56, v62, v63
	v_lshlrev_b32_e32 v62, 16, v57
	v_and_b32_e32 v63, 0xffff0000, v57
	v_pk_mul_f32 v[60:61], v[60:61], v[62:63]
	v_pk_mul_f32 v[62:63], v[122:123], v[144:145] op_sel_hi:[1,0]
	v_cvt_pk_bf16_f32 v57, v60, v61
	v_lshlrev_b32_e32 v60, 16, v58
	v_and_b32_e32 v61, 0xffff0000, v58
	v_pk_mul_f32 v[60:61], v[72:73], v[60:61]
	v_lshlrev_b32_e32 v72, 16, v52
	v_cvt_pk_bf16_f32 v58, v60, v61
	v_lshlrev_b32_e32 v60, 16, v59
	v_and_b32_e32 v61, 0xffff0000, v59
	v_pk_mul_f32 v[60:61], v[74:75], v[60:61]
	v_and_b32_e32 v73, 0xffff0000, v52
	v_cvt_pk_bf16_f32 v59, v60, v61
	global_store_dwordx4 v[126:127], v[56:59], off offset:2576
	v_pk_mul_f32 v[60:61], v[124:125], v[144:145] op_sel_hi:[1,0]
	s_nop 0
	v_pk_mul_f32 v[58:59], v[88:89], v[144:145] op_sel_hi:[1,0]
	v_pk_mul_f32 v[56:57], v[90:91], v[144:145] op_sel_hi:[1,0]
	v_pk_mul_f32 v[58:59], v[58:59], v[72:73]
	s_nop 0
	v_cvt_pk_bf16_f32 v52, v58, v59
	v_lshlrev_b32_e32 v58, 16, v53
	v_and_b32_e32 v59, 0xffff0000, v53
	v_pk_mul_f32 v[56:57], v[56:57], v[58:59]
	v_pk_mul_f32 v[58:59], v[114:115], v[144:145] op_sel_hi:[1,0]
	v_cvt_pk_bf16_f32 v53, v56, v57
	v_lshlrev_b32_e32 v56, 16, v54
	v_and_b32_e32 v57, 0xffff0000, v54
	v_pk_mul_f32 v[56:57], v[62:63], v[56:57]
	s_nop 0
	v_cvt_pk_bf16_f32 v54, v56, v57
	v_lshlrev_b32_e32 v56, 16, v55
	v_and_b32_e32 v57, 0xffff0000, v55
	v_pk_mul_f32 v[56:57], v[60:61], v[56:57]
	v_lshlrev_b32_e32 v60, 16, v48
	v_cvt_pk_bf16_f32 v55, v56, v57
	global_store_dwordx4 v[126:127], v[52:55], off offset:2592
	v_and_b32_e32 v61, 0xffff0000, v48
	v_pk_mul_f32 v[56:57], v[116:117], v[144:145] op_sel_hi:[1,0]
	v_pk_mul_f32 v[54:55], v[68:69], v[144:145] op_sel_hi:[1,0]
	v_pk_mul_f32 v[52:53], v[70:71], v[144:145] op_sel_hi:[1,0]
	v_pk_mul_f32 v[54:55], v[54:55], v[60:61]
	s_nop 0
	v_cvt_pk_bf16_f32 v48, v54, v55
	v_lshlrev_b32_e32 v54, 16, v49
	v_and_b32_e32 v55, 0xffff0000, v49
	v_pk_mul_f32 v[52:53], v[52:53], v[54:55]
	v_pk_mul_f32 v[54:55], v[102:103], v[144:145] op_sel_hi:[1,0]
	v_cvt_pk_bf16_f32 v49, v52, v53
	v_lshlrev_b32_e32 v52, 16, v50
	v_and_b32_e32 v53, 0xffff0000, v50
	v_pk_mul_f32 v[52:53], v[58:59], v[52:53]
	s_nop 0
	v_cvt_pk_bf16_f32 v50, v52, v53
	v_lshlrev_b32_e32 v52, 16, v51
	v_and_b32_e32 v53, 0xffff0000, v51
	v_pk_mul_f32 v[52:53], v[56:57], v[52:53]
	s_waitcnt vmcnt(25)
	v_lshlrev_b32_e32 v56, 16, v44
	v_cvt_pk_bf16_f32 v51, v52, v53
	global_store_dwordx4 v[126:127], v[48:51], off offset:2608
	v_and_b32_e32 v57, 0xffff0000, v44
	v_pk_mul_f32 v[52:53], v[104:105], v[144:145] op_sel_hi:[1,0]
	v_pk_mul_f32 v[50:51], v[106:107], v[144:145] op_sel_hi:[1,0]
	v_pk_mul_f32 v[48:49], v[108:109], v[144:145] op_sel_hi:[1,0]
	v_pk_mul_f32 v[50:51], v[50:51], v[56:57]
	s_nop 0
	v_cvt_pk_bf16_f32 v44, v50, v51
	v_lshlrev_b32_e32 v50, 16, v45
	v_and_b32_e32 v51, 0xffff0000, v45
	v_pk_mul_f32 v[48:49], v[48:49], v[50:51]
	v_pk_mul_f32 v[50:51], v[118:119], v[144:145] op_sel_hi:[1,0]
	v_cvt_pk_bf16_f32 v45, v48, v49
	v_lshlrev_b32_e32 v48, 16, v46
	v_and_b32_e32 v49, 0xffff0000, v46
	v_pk_mul_f32 v[48:49], v[54:55], v[48:49]
	s_nop 0
	v_cvt_pk_bf16_f32 v46, v48, v49
	v_lshlrev_b32_e32 v48, 16, v47
	v_and_b32_e32 v49, 0xffff0000, v47
	v_pk_mul_f32 v[48:49], v[52:53], v[48:49]
	v_lshlrev_b32_e32 v52, 16, v40
	v_cvt_pk_bf16_f32 v47, v48, v49
	global_store_dwordx4 v[126:127], v[44:47], off offset:2624
	v_and_b32_e32 v53, 0xffff0000, v40
	v_pk_mul_f32 v[48:49], v[120:121], v[144:145] op_sel_hi:[1,0]
	v_pk_mul_f32 v[46:47], v[80:81], v[144:145] op_sel_hi:[1,0]
	v_pk_mul_f32 v[44:45], v[82:83], v[144:145] op_sel_hi:[1,0]
	v_pk_mul_f32 v[46:47], v[46:47], v[52:53]
	s_nop 0
	v_cvt_pk_bf16_f32 v40, v46, v47
	v_lshlrev_b32_e32 v46, 16, v41
	v_and_b32_e32 v47, 0xffff0000, v41
	v_pk_mul_f32 v[44:45], v[44:45], v[46:47]
	v_pk_mul_f32 v[46:47], v[110:111], v[144:145] op_sel_hi:[1,0]
	v_cvt_pk_bf16_f32 v41, v44, v45
	v_lshlrev_b32_e32 v44, 16, v42
	v_and_b32_e32 v45, 0xffff0000, v42
	v_pk_mul_f32 v[44:45], v[50:51], v[44:45]
	s_nop 0
	v_cvt_pk_bf16_f32 v42, v44, v45
	v_lshlrev_b32_e32 v44, 16, v43
	v_and_b32_e32 v45, 0xffff0000, v43
	v_pk_mul_f32 v[44:45], v[48:49], v[44:45]
	v_lshlrev_b32_e32 v48, 16, v32
	v_cvt_pk_bf16_f32 v43, v44, v45
	global_store_dwordx4 v[126:127], v[40:43], off offset:2640
	v_and_b32_e32 v49, 0xffff0000, v32
	v_pk_mul_f32 v[44:45], v[112:113], v[144:145] op_sel_hi:[1,0]
	v_pk_mul_f32 v[42:43], v[64:65], v[144:145] op_sel_hi:[1,0]
	v_pk_mul_f32 v[40:41], v[66:67], v[144:145] op_sel_hi:[1,0]
	v_pk_mul_f32 v[42:43], v[42:43], v[48:49]
	s_nop 0
	v_cvt_pk_bf16_f32 v32, v42, v43
	v_lshlrev_b32_e32 v42, 16, v33
	v_and_b32_e32 v43, 0xffff0000, v33
	v_pk_mul_f32 v[40:41], v[40:41], v[42:43]
	v_pk_mul_f32 v[42:43], v[84:85], v[144:145] op_sel_hi:[1,0]
	v_cvt_pk_bf16_f32 v33, v40, v41
	v_lshlrev_b32_e32 v40, 16, v34
	v_and_b32_e32 v41, 0xffff0000, v34
	v_pk_mul_f32 v[40:41], v[46:47], v[40:41]
	s_nop 0
	v_cvt_pk_bf16_f32 v34, v40, v41
	v_lshlrev_b32_e32 v40, 16, v35
	v_and_b32_e32 v41, 0xffff0000, v35
	v_pk_mul_f32 v[40:41], v[44:45], v[40:41]
	v_lshlrev_b32_e32 v44, 16, v24
	v_cvt_pk_bf16_f32 v35, v40, v41
	global_store_dwordx4 v[126:127], v[32:35], off offset:2656
	v_and_b32_e32 v45, 0xffff0000, v24
	v_pk_mul_f32 v[40:41], v[86:87], v[144:145] op_sel_hi:[1,0]
	v_pk_mul_f32 v[34:35], v[92:93], v[144:145] op_sel_hi:[1,0]
	v_pk_mul_f32 v[32:33], v[94:95], v[144:145] op_sel_hi:[1,0]
	v_pk_mul_f32 v[34:35], v[34:35], v[44:45]
	s_nop 0
	v_cvt_pk_bf16_f32 v24, v34, v35
	v_lshlrev_b32_e32 v34, 16, v25
	v_and_b32_e32 v35, 0xffff0000, v25
	v_pk_mul_f32 v[32:33], v[32:33], v[34:35]
	s_nop 0
	v_cvt_pk_bf16_f32 v25, v32, v33
	v_lshlrev_b32_e32 v32, 16, v26
	v_and_b32_e32 v33, 0xffff0000, v26
	v_pk_mul_f32 v[32:33], v[42:43], v[32:33]
	s_nop 0
	v_cvt_pk_bf16_f32 v26, v32, v33
	v_lshlrev_b32_e32 v32, 16, v27
	v_and_b32_e32 v33, 0xffff0000, v27
	v_pk_mul_f32 v[32:33], v[40:41], v[32:33]
	s_nop 0
	v_cvt_pk_bf16_f32 v27, v32, v33
	global_store_dwordx4 v[126:127], v[24:27], off offset:2672
	s_waitcnt lgkmcnt(0)
	s_barrier
	s_waitcnt vmcnt(16)
	s_waitcnt lgkmcnt(0)
	s_barrier
	s_branch .LBB0_974

.LBB0_983:
	s_waitcnt lgkmcnt(0)
	s_barrier
	s_waitcnt vmcnt(0)
	s_waitcnt lgkmcnt(0)
	s_barrier
	s_cmp_gt_u32 s30, 61
	s_cbranch_scc1 .LBB0_982
	s_bitcmp1_b32 s30, 0
	s_cselect_b32 s31, 0xe000, 0
	s_add_i32 s44, s39, s31
	v_lshl_add_u64 v[4:5], v[2:3], 0, s[2:3]
	s_mov_b64 s[40:41], 0x3fe58000
	v_lshl_add_u64 v[6:7], v[4:5], 0, s[40:41]
	s_mov_b64 s[40:41], 0x40a58000
	s_mov_b32 m0, s44
	s_add_i32 s31, s38, s31
	v_lshl_add_u64 v[8:9], v[4:5], 0, s[40:41]
	s_mov_b64 s[40:41], 0x41658000
	global_load_lds_dwordx4 v[6:7], off
	s_add_i32 m0, s31, 0x2000
	v_lshl_add_u64 v[10:11], v[4:5], 0, s[40:41]
	global_load_lds_dwordx4 v[8:9], off
	s_add_i32 m0, s31, 0x6000
	s_mov_b64 s[40:41], 0x3fe58400
	global_load_lds_dwordx4 v[10:11], off
	v_lshl_add_u64 v[6:7], v[4:5], 0, s[40:41]
	s_add_i32 m0, s44, 0x400
	s_mov_b64 s[40:41], 0x40a58400
	global_load_lds_dwordx4 v[6:7], off
	v_lshl_add_u64 v[6:7], v[4:5], 0, s[40:41]
	s_add_i32 m0, s31, 0x2400
	s_mov_b64 s[40:41], 0x41658400
	global_load_lds_dwordx4 v[6:7], off
	v_lshl_add_u64 v[6:7], v[4:5], 0, s[40:41]
	s_add_i32 m0, s31, 0x6400
	s_mov_b64 s[40:41], 0x3fe59000
	global_load_lds_dwordx4 v[6:7], off
	v_lshl_add_u64 v[6:7], v[4:5], 0, s[40:41]
	s_add_i32 m0, s44, 0x1000
	s_mov_b64 s[40:41], 0x40a59000
	v_lshl_add_u64 v[8:9], v[4:5], 0, s[40:41]
	s_mov_b64 s[40:41], 0x41659000
	global_load_lds_dwordx4 v[6:7], off
	s_add_i32 m0, s31, 0x3000
	v_lshl_add_u64 v[10:11], v[4:5], 0, s[40:41]
	global_load_lds_dwordx4 v[8:9], off
	s_add_i32 m0, s31, 0x7000
	s_mov_b64 s[40:41], 0x3fe59400
	global_load_lds_dwordx4 v[10:11], off
	v_lshl_add_u64 v[6:7], v[4:5], 0, s[40:41]
	s_add_i32 m0, s44, 0x1400
	s_mov_b64 s[40:41], 0x40a59400
	global_load_lds_dwordx4 v[6:7], off
	v_lshl_add_u64 v[6:7], v[4:5], 0, s[40:41]
	s_add_i32 m0, s31, 0x3400
	s_mov_b64 s[40:41], 0x41659400
	global_load_lds_dwordx4 v[6:7], off
	v_lshl_add_u64 v[6:7], v[4:5], 0, s[40:41]
	s_add_i32 m0, s31, 0x7400
	s_mov_b64 s[40:41], 0x3fe5a000
	global_load_lds_dwordx4 v[6:7], off
	v_lshl_add_u64 v[6:7], v[4:5], 0, s[40:41]
	s_mov_b64 s[40:41], 0x40a5a000
	s_mov_b32 m0, s31
	v_lshl_add_u64 v[8:9], v[4:5], 0, s[40:41]
	s_mov_b64 s[40:41], 0x4165a000
	s_add_i32 m0, s31, 0x4000
	v_lshl_add_u64 v[10:11], v[4:5], 0, s[40:41]
	s_add_i32 m0, s31, 0x8000
	s_mov_b64 s[40:41], 0x3fe5a400
	v_lshl_add_u64 v[6:7], v[4:5], 0, s[40:41]
	s_add_i32 m0, s31, 0x400
	s_mov_b64 s[40:41], 0x40a5a400
	v_lshl_add_u64 v[6:7], v[4:5], 0, s[40:41]
	s_add_i32 m0, s31, 0x4400
	s_mov_b64 s[40:41], 0x4165a400
	v_lshl_add_u64 v[6:7], v[4:5], 0, s[40:41]
	s_add_i32 m0, s31, 0x8400
	s_mov_b64 s[40:41], 0x3fe5b000
	v_lshl_add_u64 v[6:7], v[4:5], 0, s[40:41]
	s_mov_b64 s[40:41], 0x40a5b000
	s_add_i32 m0, s31, 0x1000
	v_lshl_add_u64 v[8:9], v[4:5], 0, s[40:41]
	s_mov_b64 s[40:41], 0x4165b000
	s_add_i32 m0, s31, 0x5000
	v_lshl_add_u64 v[10:11], v[4:5], 0, s[40:41]
	s_add_i32 m0, s31, 0x9000
	s_mov_b64 s[40:41], 0x3fe5b400
	v_lshl_add_u64 v[6:7], v[4:5], 0, s[40:41]
	s_add_i32 m0, s31, 0x1400
	s_mov_b64 s[40:41], 0x40a5b400
	v_lshl_add_u64 v[6:7], v[4:5], 0, s[40:41]
	s_add_i32 m0, s31, 0x5400
	s_mov_b64 s[40:41], 0x4165b400
	v_lshl_add_u64 v[4:5], v[4:5], 0, s[40:41]
	s_add_i32 m0, s31, 0x9400
	s_mov_b64 s[40:41], 0x42254000
	v_lshl_add_u64 v[4:5], v[0:1], 0, s[2:3]
	v_lshl_add_u64 v[6:7], v[4:5], 0, s[40:41]
	s_add_i32 m0, s31, 0xa000
	s_mov_b64 s[40:41], 0x42254400
	global_load_lds_dwordx4 v[6:7], off
	v_lshl_add_u64 v[6:7], v[4:5], 0, s[40:41]
	s_add_i32 m0, s31, 0xa400
	s_mov_b64 s[40:41], 0x42255000
	global_load_lds_dwordx4 v[6:7], off
	v_lshl_add_u64 v[6:7], v[4:5], 0, s[40:41]
	s_add_i32 m0, s31, 0xb000
	s_mov_b64 s[40:41], 0x42255400
	v_lshl_add_u64 v[4:5], v[4:5], 0, s[40:41]
	s_add_i32 m0, s31, 0xb400
	s_nop 0
	s_branch .LBB0_982

.LBB0_988:
	v_lshl_add_u64 v[64:65], s[30:31], 0, v[162:163]
	v_lshl_add_u64 v[66:67], s[30:31], 0, v[160:161]
	v_lshl_add_u64 v[68:69], s[30:31], 0, v[158:159]
	v_lshl_add_u64 v[70:71], s[30:31], 0, v[156:157]
	global_load_dwordx2 v[198:199], v[64:65], off
	global_load_dwordx2 v[194:195], v[66:67], off
	global_load_dwordx2 v[190:191], v[68:69], off
	global_load_dwordx2 v[180:181], v[70:71], off
	v_lshl_add_u64 v[64:65], s[30:31], 0, v[154:155]
	v_lshl_add_u64 v[66:67], s[30:31], 0, v[152:153]
	v_lshl_add_u64 v[68:69], s[30:31], 0, v[150:151]
	v_lshl_add_u64 v[70:71], s[30:31], 0, v[148:149]
	global_load_dwordx2 v[196:197], v[64:65], off
	global_load_dwordx2 v[192:193], v[66:67], off
	global_load_dwordx2 v[188:189], v[68:69], off
	global_load_dwordx2 v[186:187], v[70:71], off
	s_add_i32 s2, s1, 1
	ds_read_b128 v[92:95], v101 offset:16384
	ds_read_b128 v[102:105], v101 offset:17408
	ds_read_b128 v[106:109], v101 offset:18432
	ds_read_b128 v[110:113], v101 offset:19456
	ds_read_b128 v[118:121], v101 offset:20480
	ds_read_b128 v[122:125], v101 offset:21504
	ds_read_b128 v[126:129], v101 offset:22528
	ds_read_b128 v[130:133], v101 offset:23552
	v_cvt_pk_bf16_f32 v64, v0, v1
	v_cvt_pk_bf16_f32 v65, v2, v3
	v_cvt_pk_bf16_f32 v66, v4, v5
	v_cvt_pk_bf16_f32 v67, v6, v7
	v_cvt_pk_bf16_f32 v68, v8, v9
	v_cvt_pk_bf16_f32 v69, v10, v11
	v_cvt_pk_bf16_f32 v70, v12, v13
	v_cvt_pk_bf16_f32 v71, v14, v15
	v_cvt_pk_bf16_f32 v72, v16, v17
	v_cvt_pk_bf16_f32 v73, v18, v19
	v_cvt_pk_bf16_f32 v74, v24, v25
	v_cvt_pk_bf16_f32 v75, v26, v27
	v_cvt_pk_bf16_f32 v76, v32, v33
	v_cvt_pk_bf16_f32 v77, v34, v35
	v_cvt_pk_bf16_f32 v78, v40, v41
	v_cvt_pk_bf16_f32 v79, v42, v43
	v_cvt_pk_bf16_f32 v80, v20, v21
	v_cvt_pk_bf16_f32 v81, v22, v23
	v_cvt_pk_bf16_f32 v82, v28, v29
	v_cvt_pk_bf16_f32 v83, v30, v31
	v_cvt_pk_bf16_f32 v84, v36, v37
	v_cvt_pk_bf16_f32 v85, v38, v39
	v_cvt_pk_bf16_f32 v86, v44, v45
	v_cvt_pk_bf16_f32 v87, v46, v47
	v_cvt_pk_bf16_f32 v88, v48, v49
	v_cvt_pk_bf16_f32 v89, v50, v51
	v_cvt_pk_bf16_f32 v90, v52, v53
	v_cvt_pk_bf16_f32 v91, v54, v55
	v_cvt_pk_bf16_f32 v114, v56, v57
	v_cvt_pk_bf16_f32 v115, v58, v59
	v_cvt_pk_bf16_f32 v116, v60, v61
	v_cvt_pk_bf16_f32 v117, v62, v63
	v_readlane_b32 s0, v96, s1
	s_waitcnt lgkmcnt(7)
	v_mfma_f32_16x16x32_bf16 v[204:207], v[92:95], v[64:67], 0
	v_mfma_f32_16x16x32_bf16 v[92:95], v[92:95], v[80:83], 0
	s_waitcnt lgkmcnt(6)
	v_mfma_f32_16x16x32_bf16 v[204:207], v[102:105], v[68:71], v[204:207]
	v_mfma_f32_16x16x32_bf16 v[92:95], v[102:105], v[84:87], v[92:95]
	s_waitcnt lgkmcnt(5)
	v_mfma_f32_16x16x32_bf16 v[102:105], v[106:109], v[72:75], v[204:207]
	v_mfma_f32_16x16x32_bf16 v[106:109], v[106:109], v[88:91], v[92:95]
	s_waitcnt lgkmcnt(4)
	v_mfma_f32_16x16x32_bf16 v[92:95], v[110:113], v[76:79], v[102:105]
	v_mfma_f32_16x16x32_bf16 v[102:105], v[110:113], v[114:117], v[106:109]
	s_nop 0
	ds_read_b128 v[204:207], v101 offset:24576
	ds_read_b128 v[208:211], v101 offset:25600
	ds_read_b128 v[212:215], v101 offset:26624
	ds_read_b128 v[216:219], v101 offset:27648
	s_waitcnt lgkmcnt(7)
	v_mfma_f32_16x16x32_bf16 v[106:109], v[118:121], v[64:67], 0
	v_mfma_f32_16x16x32_bf16 v[110:113], v[118:121], v[80:83], 0
	s_waitcnt lgkmcnt(6)
	v_mfma_f32_16x16x32_bf16 v[106:109], v[122:125], v[68:71], v[106:109]
	v_mfma_f32_16x16x32_bf16 v[110:113], v[122:125], v[84:87], v[110:113]
	s_waitcnt lgkmcnt(5)
	v_mfma_f32_16x16x32_bf16 v[106:109], v[126:129], v[72:75], v[106:109]
	v_mfma_f32_16x16x32_bf16 v[110:113], v[126:129], v[88:91], v[110:113]
	s_waitcnt lgkmcnt(4)
	v_mfma_f32_16x16x32_bf16 v[106:109], v[130:133], v[76:79], v[106:109]
	v_mfma_f32_16x16x32_bf16 v[110:113], v[130:133], v[114:117], v[110:113]
	ds_read_b128 v[126:129], v101 offset:28672
	ds_read_b128 v[130:133], v101 offset:29696
	ds_read_b128 v[220:223], v101 offset:30720
	ds_read_b128 v[234:237], v101 offset:31744
	s_waitcnt lgkmcnt(7)
	v_mfma_f32_16x16x32_bf16 v[118:121], v[204:207], v[64:67], 0
	v_mfma_f32_16x16x32_bf16 v[122:125], v[204:207], v[80:83], 0
	s_waitcnt lgkmcnt(6)
	v_mfma_f32_16x16x32_bf16 v[118:121], v[208:211], v[68:71], v[118:121]
	v_mfma_f32_16x16x32_bf16 v[122:125], v[208:211], v[84:87], v[122:125]
	s_waitcnt lgkmcnt(5)
	v_mfma_f32_16x16x32_bf16 v[118:121], v[212:215], v[72:75], v[118:121]
	v_mfma_f32_16x16x32_bf16 v[122:125], v[212:215], v[88:91], v[122:125]
	s_waitcnt lgkmcnt(4)
	v_mfma_f32_16x16x32_bf16 v[118:121], v[216:219], v[76:79], v[118:121]
	v_mfma_f32_16x16x32_bf16 v[122:125], v[216:219], v[114:117], v[122:125]
	ds_read_b128 v[204:207], v101
	ds_read_b128 v[208:211], v101 offset:1024
	ds_read_b128 v[212:215], v101 offset:2048
	ds_read_b128 v[216:219], v101 offset:3072
	s_waitcnt lgkmcnt(7)
	v_mfma_f32_16x16x32_bf16 v[238:241], v[126:129], v[64:67], 0
	v_mfma_f32_16x16x32_bf16 v[126:129], v[126:129], v[80:83], 0
	s_waitcnt lgkmcnt(6)
	v_mfma_f32_16x16x32_bf16 v[238:241], v[130:133], v[68:71], v[238:241]
	v_mfma_f32_16x16x32_bf16 v[126:129], v[130:133], v[84:87], v[126:129]
	s_waitcnt lgkmcnt(5)
	v_mfma_f32_16x16x32_bf16 v[130:133], v[220:223], v[72:75], v[238:241]
	v_mfma_f32_16x16x32_bf16 v[220:223], v[220:223], v[88:91], v[126:129]
	s_waitcnt lgkmcnt(4)
	v_mfma_f32_16x16x32_bf16 v[126:129], v[234:237], v[76:79], v[130:133]
	v_mfma_f32_16x16x32_bf16 v[130:133], v[234:237], v[114:117], v[220:223]
	s_nop 4
	ds_read_b128 v[220:223], v101 offset:4096
	ds_read_b128 v[234:237], v101 offset:5120
	ds_read_b128 v[238:241], v101 offset:6144
	ds_read_b128 v[242:245], v101 offset:7168
	s_waitcnt lgkmcnt(7)
	v_mfma_f32_16x16x32_bf16 v[246:249], v[204:207], v[64:67], 0
	s_waitcnt vmcnt(15)
	v_lshlrev_b32_e32 v203, 16, v178
	v_and_b32_e32 v178, 0xffff0000, v178
	v_mfma_f32_16x16x32_bf16 v[204:207], v[204:207], v[80:83], 0
	s_waitcnt lgkmcnt(6)
	v_mfma_f32_16x16x32_bf16 v[246:249], v[208:211], v[68:71], v[246:249]
	v_mfma_f32_16x16x32_bf16 v[204:207], v[208:211], v[84:87], v[204:207]
	s_waitcnt lgkmcnt(5)
	v_mfma_f32_16x16x32_bf16 v[208:211], v[212:215], v[72:75], v[246:249]
	v_mfma_f32_16x16x32_bf16 v[204:207], v[212:215], v[88:91], v[204:207]
	v_lshlrev_b32_e32 v212, 16, v179
	v_and_b32_e32 v179, 0xffff0000, v179
	s_waitcnt lgkmcnt(4)
	v_mfma_f32_16x16x32_bf16 v[208:211], v[216:219], v[76:79], v[208:211]
	v_mfma_f32_16x16x32_bf16 v[204:207], v[216:219], v[114:117], v[204:207]
	s_nop 6
	v_sub_f32_e32 v224, v179, v211
	v_sub_f32_e32 v233, v178, v209
	s_waitcnt vmcnt(11)
	v_lshlrev_b32_e32 v178, 16, v176
	v_and_b32_e32 v176, 0xffff0000, v176
	v_lshlrev_b32_e32 v179, 16, v177
	v_and_b32_e32 v177, 0xffff0000, v177
	v_sub_f32_e32 v225, v212, v210
	v_sub_f32_e32 v203, v203, v208
	v_sub_f32_e32 v246, v177, v207
	v_sub_f32_e32 v247, v179, v206
	v_sub_f32_e32 v248, v176, v205
	v_sub_f32_e32 v249, v178, v204
	ds_read_b128 v[176:179], v101 offset:8192
	ds_read_b128 v[204:207], v101 offset:9216
	ds_read_b128 v[208:211], v101 offset:10240
	ds_read_b128 v[212:215], v101 offset:11264
	s_waitcnt lgkmcnt(7)
	v_mfma_f32_16x16x32_bf16 v[216:219], v[220:223], v[64:67], 0
	v_mfma_f32_16x16x32_bf16 v[220:223], v[220:223], v[80:83], 0
	s_waitcnt lgkmcnt(6)
	v_mfma_f32_16x16x32_bf16 v[216:219], v[234:237], v[68:71], v[216:219]
	v_mfma_f32_16x16x32_bf16 v[220:223], v[234:237], v[84:87], v[220:223]
	v_lshlrev_b32_e32 v234, 16, v174
	v_and_b32_e32 v174, 0xffff0000, v174
	v_lshlrev_b32_e32 v235, 16, v175
	s_waitcnt lgkmcnt(5)
	v_mfma_f32_16x16x32_bf16 v[216:219], v[238:241], v[72:75], v[216:219]
	v_and_b32_e32 v175, 0xffff0000, v175
	v_mfma_f32_16x16x32_bf16 v[220:223], v[238:241], v[88:91], v[220:223]
	s_waitcnt lgkmcnt(4)
	v_mfma_f32_16x16x32_bf16 v[216:219], v[242:245], v[76:79], v[216:219]
	v_mfma_f32_16x16x32_bf16 v[220:223], v[242:245], v[114:117], v[220:223]
	s_nop 6
	v_sub_f32_e32 v242, v175, v219
	v_sub_f32_e32 v244, v174, v217
	s_waitcnt vmcnt(10)
	v_lshlrev_b32_e32 v174, 16, v172
	v_and_b32_e32 v172, 0xffff0000, v172
	v_lshlrev_b32_e32 v175, 16, v173
	v_and_b32_e32 v173, 0xffff0000, v173
	v_sub_f32_e32 v243, v235, v218
	v_sub_f32_e32 v245, v234, v216
	v_sub_f32_e32 v250, v173, v223
	v_sub_f32_e32 v251, v175, v222
	v_sub_f32_e32 v227, v172, v221
	v_sub_f32_e32 v182, v174, v220
	ds_read_b128 v[172:175], v101 offset:12288
	ds_read_b128 v[216:219], v101 offset:13312
	ds_read_b128 v[220:223], v101 offset:14336
	ds_read_b128 v[234:237], v101 offset:15360
	s_waitcnt lgkmcnt(7)
	v_mfma_f32_16x16x32_bf16 v[238:241], v[176:179], v[64:67], 0
	v_lshlrev_b32_e32 v183, 16, v170
	v_and_b32_e32 v170, 0xffff0000, v170
	v_mfma_f32_16x16x32_bf16 v[176:179], v[176:179], v[80:83], 0
	s_waitcnt lgkmcnt(6)
	v_mfma_f32_16x16x32_bf16 v[238:241], v[204:207], v[68:71], v[238:241]
	v_mfma_f32_16x16x32_bf16 v[176:179], v[204:207], v[84:87], v[176:179]
	s_waitcnt lgkmcnt(5)
	v_mfma_f32_16x16x32_bf16 v[204:207], v[208:211], v[72:75], v[238:241]
	v_mfma_f32_16x16x32_bf16 v[176:179], v[208:211], v[88:91], v[176:179]
	v_lshlrev_b32_e32 v208, 16, v171
	v_and_b32_e32 v171, 0xffff0000, v171
	s_waitcnt lgkmcnt(4)
	v_mfma_f32_16x16x32_bf16 v[204:207], v[212:215], v[76:79], v[204:207]
	v_mfma_f32_16x16x32_bf16 v[176:179], v[212:215], v[114:117], v[176:179]
	s_nop 6
	v_sub_f32_e32 v207, v171, v207
	v_sub_f32_e32 v205, v170, v205
	s_waitcnt vmcnt(9)
	v_lshlrev_b32_e32 v170, 16, v168
	v_and_b32_e32 v168, 0xffff0000, v168
	v_lshlrev_b32_e32 v171, 16, v169
	v_and_b32_e32 v169, 0xffff0000, v169
	v_sub_f32_e32 v206, v208, v206
	v_sub_f32_e32 v183, v183, v204
	v_sub_f32_e32 v204, v169, v179
	v_sub_f32_e32 v208, v171, v178
	v_sub_f32_e32 v209, v168, v177
	v_sub_f32_e32 v210, v170, v176
	ds_read_b128 v[168:171], v101 offset:49152
	ds_read_b128 v[176:179], v101 offset:50176
	s_waitcnt lgkmcnt(5)
	v_mfma_f32_16x16x32_bf16 v[64:67], v[172:175], v[64:67], 0
	s_waitcnt lgkmcnt(4)
	v_mfma_f32_16x16x32_bf16 v[64:67], v[216:219], v[68:71], v[64:67]
	v_lshlrev_b32_e32 v68, 16, v165
	v_and_b32_e32 v69, 0xffff0000, v165
	v_lshlrev_b32_e32 v70, 16, v164
	s_waitcnt lgkmcnt(3)
	v_mfma_f32_16x16x32_bf16 v[64:67], v[220:223], v[72:75], v[64:67]
	v_and_b32_e32 v71, 0xffff0000, v164
	s_waitcnt vmcnt(8)
	v_lshlrev_b32_e32 v74, 16, v166
	v_and_b32_e32 v75, 0xffff0000, v167
	v_mfma_f32_16x16x32_bf16 v[80:83], v[172:175], v[80:83], 0
	s_waitcnt lgkmcnt(2)
	v_mfma_f32_16x16x32_bf16 v[64:67], v[234:237], v[76:79], v[64:67]
	v_cvt_pk_bf16_f32 v76, v210, v209
	v_cvt_pk_bf16_f32 v77, v208, v204
	s_nop 5
	v_sub_f32_e32 v72, v69, v67
	v_sub_f32_e32 v73, v68, v66
	v_mfma_f32_16x16x32_bf16 v[66:69], v[216:219], v[84:87], v[80:83]
	v_sub_f32_e32 v71, v71, v65
	v_sub_f32_e32 v70, v70, v64
	v_cvt_pk_bf16_f32 v70, v70, v71
	v_mfma_f32_16x16x32_bf16 v[64:67], v[220:223], v[88:91], v[66:69]
	v_cvt_pk_bf16_f32 v71, v73, v72
	v_cvt_pk_bf16_f32 v72, v249, v248
	v_cvt_pk_bf16_f32 v73, v247, v246
	v_mfma_f32_16x16x32_bf16 v[64:67], v[234:237], v[114:117], v[64:67]
	v_and_b32_e32 v68, 0xffff0000, v166
	v_lshlrev_b32_e32 v69, 16, v167
	s_nop 5
	v_sub_f32_e32 v79, v75, v67
	v_sub_f32_e32 v80, v69, v66
	v_sub_f32_e32 v78, v68, v65
	v_sub_f32_e32 v81, v74, v64
	v_cvt_pk_bf16_f32 v64, v203, v233
	v_cvt_pk_bf16_f32 v65, v225, v224
	v_cvt_pk_bf16_f32 v66, v245, v244
	v_cvt_pk_bf16_f32 v67, v243, v242
	v_cvt_pk_bf16_f32 v68, v183, v205
	v_cvt_pk_bf16_f32 v69, v206, v207
	v_cvt_pk_bf16_f32 v74, v182, v227
	v_cvt_pk_bf16_f32 v75, v251, v250
	v_cvt_pk_bf16_f32 v78, v81, v78
	v_cvt_pk_bf16_f32 v79, v80, v79
	ds_read_b128 v[80:83], v101 offset:51200
	ds_read_b128 v[84:87], v101 offset:52224
	ds_read_b128 v[204:207], v101 offset:53248
	ds_read_b128 v[208:211], v101 offset:54272
	s_waitcnt lgkmcnt(5)
	v_mfma_f32_16x16x32_bf16 v[88:91], v[168:171], v[64:67], v[92:95]
	v_mfma_f32_16x16x32_bf16 v[92:95], v[168:171], v[72:75], v[102:105]
	s_waitcnt lgkmcnt(4)
	v_mfma_f32_16x16x32_bf16 v[88:91], v[176:179], v[68:71], v[88:91]
	v_mfma_f32_16x16x32_bf16 v[92:95], v[176:179], v[76:79], v[92:95]
	ds_read_b128 v[212:215], v101 offset:55296
	ds_read_b128 v[216:219], v101 offset:56320
	s_waitcnt lgkmcnt(5)
	v_mfma_f32_16x16x32_bf16 v[106:109], v[80:83], v[64:67], v[106:109]
	v_mfma_f32_16x16x32_bf16 v[80:83], v[80:83], v[72:75], v[110:113]
	s_waitcnt lgkmcnt(4)
	v_mfma_f32_16x16x32_bf16 v[106:109], v[84:87], v[68:71], v[106:109]
	v_mfma_f32_16x16x32_bf16 v[80:83], v[84:87], v[76:79], v[80:83]
	ds_read_b128 v[220:223], v101 offset:32768
	ds_read_b128 v[234:237], v101 offset:33792
	s_waitcnt lgkmcnt(5)
	v_mfma_f32_16x16x32_bf16 v[118:121], v[204:207], v[64:67], v[118:121]
	v_mfma_f32_16x16x32_bf16 v[102:105], v[204:207], v[72:75], v[122:125]
	s_waitcnt lgkmcnt(4)
	v_mfma_f32_16x16x32_bf16 v[118:121], v[208:211], v[68:71], v[118:121]
	v_mfma_f32_16x16x32_bf16 v[102:105], v[208:211], v[76:79], v[102:105]
	ds_read_b128 v[204:207], v101 offset:34816
	ds_read_b128 v[208:211], v101 offset:35840
	s_waitcnt lgkmcnt(5)
	v_mfma_f32_16x16x32_bf16 v[126:129], v[212:215], v[64:67], v[126:129]
	v_mfma_f32_16x16x32_bf16 v[84:87], v[212:215], v[72:75], v[130:133]
	s_waitcnt lgkmcnt(4)
	v_mfma_f32_16x16x32_bf16 v[126:129], v[216:219], v[68:71], v[126:129]
	v_mfma_f32_16x16x32_bf16 v[84:87], v[216:219], v[76:79], v[84:87]
	ds_read_b128 v[212:215], v101 offset:36864
	ds_read_b128 v[216:219], v101 offset:37888
	v_pk_mul_f32 v[2:3], v[2:3], s[0:1] op_sel_hi:[1,0]
	v_pk_mul_f32 v[0:1], v[0:1], s[0:1] op_sel_hi:[1,0]
	v_pk_mul_f32 v[22:23], v[22:23], s[0:1] op_sel_hi:[1,0]
	v_pk_mul_f32 v[20:21], v[20:21], s[0:1] op_sel_hi:[1,0]
	s_waitcnt lgkmcnt(5)
	v_mfma_f32_16x16x32_bf16 v[0:3], v[220:223], v[64:67], v[0:3]
	v_mfma_f32_16x16x32_bf16 v[114:117], v[220:223], v[72:75], v[20:23]
	s_waitcnt lgkmcnt(4)
	v_mfma_f32_16x16x32_bf16 v[20:23], v[234:237], v[68:71], v[0:3]
	v_mfma_f32_16x16x32_bf16 v[0:3], v[234:237], v[76:79], v[114:117]
	ds_read_b128 v[220:223], v101 offset:38912
	ds_read_b128 v[234:237], v101 offset:39936
	v_pk_mul_f32 v[6:7], v[6:7], s[0:1] op_sel_hi:[1,0]
	v_pk_mul_f32 v[4:5], v[4:5], s[0:1] op_sel_hi:[1,0]
	v_pk_mul_f32 v[30:31], v[30:31], s[0:1] op_sel_hi:[1,0]
	v_pk_mul_f32 v[28:29], v[28:29], s[0:1] op_sel_hi:[1,0]
	s_waitcnt lgkmcnt(5)
	v_mfma_f32_16x16x32_bf16 v[4:7], v[204:207], v[64:67], v[4:7]
	v_mfma_f32_16x16x32_bf16 v[110:113], v[204:207], v[72:75], v[28:31]
	s_waitcnt lgkmcnt(4)
	v_mfma_f32_16x16x32_bf16 v[28:31], v[208:211], v[68:71], v[4:7]
	v_mfma_f32_16x16x32_bf16 v[4:7], v[208:211], v[76:79], v[110:113]
	ds_read_b128 v[204:207], v101 offset:40960
	ds_read_b128 v[208:211], v101 offset:41984
	v_pk_mul_f32 v[10:11], v[10:11], s[0:1] op_sel_hi:[1,0]
	v_pk_mul_f32 v[8:9], v[8:9], s[0:1] op_sel_hi:[1,0]
	v_pk_mul_f32 v[38:39], v[38:39], s[0:1] op_sel_hi:[1,0]
	v_pk_mul_f32 v[36:37], v[36:37], s[0:1] op_sel_hi:[1,0]
	s_waitcnt lgkmcnt(5)
	v_mfma_f32_16x16x32_bf16 v[8:11], v[212:215], v[64:67], v[8:11]
	v_mfma_f32_16x16x32_bf16 v[114:117], v[212:215], v[72:75], v[36:39]
	s_waitcnt lgkmcnt(4)
	v_mfma_f32_16x16x32_bf16 v[36:39], v[216:219], v[68:71], v[8:11]
	v_mfma_f32_16x16x32_bf16 v[8:11], v[216:219], v[76:79], v[114:117]
	ds_read_b128 v[212:215], v101 offset:43008
	ds_read_b128 v[216:219], v101 offset:44032
	v_pk_mul_f32 v[14:15], v[14:15], s[0:1] op_sel_hi:[1,0]
	v_pk_mul_f32 v[12:13], v[12:13], s[0:1] op_sel_hi:[1,0]
	v_pk_mul_f32 v[46:47], v[46:47], s[0:1] op_sel_hi:[1,0]
	v_pk_mul_f32 v[44:45], v[44:45], s[0:1] op_sel_hi:[1,0]
	s_waitcnt lgkmcnt(5)
	v_mfma_f32_16x16x32_bf16 v[12:15], v[220:223], v[64:67], v[12:15]
	v_mfma_f32_16x16x32_bf16 v[110:113], v[220:223], v[72:75], v[44:47]
	s_waitcnt lgkmcnt(4)
	v_mfma_f32_16x16x32_bf16 v[44:47], v[234:237], v[68:71], v[12:15]
	v_mfma_f32_16x16x32_bf16 v[12:15], v[234:237], v[76:79], v[110:113]
	ds_read_b128 v[220:223], v101 offset:45056
	ds_read_b128 v[234:237], v101 offset:46080
	v_pk_mul_f32 v[18:19], v[18:19], s[0:1] op_sel_hi:[1,0]
	v_pk_mul_f32 v[16:17], v[16:17], s[0:1] op_sel_hi:[1,0]
	v_pk_mul_f32 v[50:51], v[50:51], s[0:1] op_sel_hi:[1,0]
	v_pk_mul_f32 v[48:49], v[48:49], s[0:1] op_sel_hi:[1,0]
	s_waitcnt lgkmcnt(5)
	v_mfma_f32_16x16x32_bf16 v[16:19], v[204:207], v[64:67], v[16:19]
	v_mfma_f32_16x16x32_bf16 v[114:117], v[204:207], v[72:75], v[48:51]
	s_waitcnt lgkmcnt(4)
	v_mfma_f32_16x16x32_bf16 v[48:51], v[208:211], v[68:71], v[16:19]
	v_mfma_f32_16x16x32_bf16 v[16:19], v[208:211], v[76:79], v[114:117]
	ds_read_b128 v[204:207], v101 offset:47104
	ds_read_b128 v[208:211], v101 offset:48128
	v_pk_mul_f32 v[26:27], v[26:27], s[0:1] op_sel_hi:[1,0]
	v_pk_mul_f32 v[24:25], v[24:25], s[0:1] op_sel_hi:[1,0]
	v_pk_mul_f32 v[54:55], v[54:55], s[0:1] op_sel_hi:[1,0]
	v_pk_mul_f32 v[52:53], v[52:53], s[0:1] op_sel_hi:[1,0]
	s_waitcnt lgkmcnt(5)
	v_mfma_f32_16x16x32_bf16 v[24:27], v[212:215], v[64:67], v[24:27]
	v_mfma_f32_16x16x32_bf16 v[110:113], v[212:215], v[72:75], v[52:55]
	s_waitcnt lgkmcnt(4)
	v_mfma_f32_16x16x32_bf16 v[52:55], v[216:219], v[68:71], v[24:27]
	v_mfma_f32_16x16x32_bf16 v[24:27], v[216:219], v[76:79], v[110:113]
	v_pk_mul_f32 v[34:35], v[34:35], s[0:1] op_sel_hi:[1,0]
	v_pk_mul_f32 v[32:33], v[32:33], s[0:1] op_sel_hi:[1,0]
	v_pk_mul_f32 v[58:59], v[58:59], s[0:1] op_sel_hi:[1,0]
	v_pk_mul_f32 v[56:57], v[56:57], s[0:1] op_sel_hi:[1,0]
	s_waitcnt lgkmcnt(3)
	v_mfma_f32_16x16x32_bf16 v[32:35], v[220:223], v[64:67], v[32:35]
	v_mfma_f32_16x16x32_bf16 v[114:117], v[220:223], v[72:75], v[56:59]
	s_waitcnt lgkmcnt(2)
	v_mfma_f32_16x16x32_bf16 v[56:59], v[234:237], v[68:71], v[32:35]
	v_mfma_f32_16x16x32_bf16 v[32:35], v[234:237], v[76:79], v[114:117]
	v_mul_f32_e64 v42, v42, s0
	v_mul_f32_e64 v43, v43, s0
	v_pk_mul_f32 v[40:41], v[40:41], s[0:1] op_sel_hi:[1,0]
	v_pk_mul_f32 v[62:63], v[62:63], s[0:1] op_sel_hi:[1,0]
	v_pk_mul_f32 v[60:61], v[60:61], s[0:1] op_sel_hi:[1,0]
	s_waitcnt lgkmcnt(1)
	v_mfma_f32_16x16x32_bf16 v[40:43], v[204:207], v[64:67], v[40:43]
	v_mfma_f32_16x16x32_bf16 v[64:67], v[204:207], v[72:75], v[60:63]
	s_waitcnt lgkmcnt(0)
	v_mfma_f32_16x16x32_bf16 v[60:63], v[208:211], v[68:71], v[40:43]
	v_mfma_f32_16x16x32_bf16 v[40:43], v[208:211], v[76:79], v[64:67]
	s_add_i32 s36, s1, 2
	s_cmp_lt_u32 s1, 62
	s_cselect_b32 s0, s36, s2
	s_lshl_b32 s0, s0, 14
	s_add_u32 s38, s40, s0
	s_waitcnt lgkmcnt(0)
	s_barrier
	ds_write_b32 v201, v88
	ds_write_b32 v201, v89 offset:528
	ds_write_b32 v201, v90 offset:1056
	ds_write_b32 v202, v91
	ds_write_b32 v201, v106 offset:8448
	ds_write_b32 v201, v107 offset:8976
	ds_write_b32 v201, v108 offset:9504
	ds_write_b32 v201, v109 offset:10032
	ds_write_b32 v201, v118 offset:16896
	ds_write_b32 v201, v119 offset:17424
	ds_write_b32 v201, v120 offset:17952
	ds_write_b32 v201, v121 offset:18480
	ds_write_b32 v201, v126 offset:25344
	ds_write_b32 v201, v127 offset:25872
	ds_write_b32 v201, v128 offset:26400
	ds_write_b32 v201, v129 offset:26928
	ds_write_b32 v201, v92 offset:64
	ds_write_b32 v201, v93 offset:592
	ds_write_b32 v201, v94 offset:1120
	ds_write_b32 v202, v95 offset:64
	ds_write_b32 v201, v80 offset:8512
	ds_write_b32 v201, v81 offset:9040
	ds_write_b32 v201, v82 offset:9568
	ds_write_b32 v201, v83 offset:10096
	ds_write_b32 v201, v102 offset:16960
	ds_write_b32 v201, v103 offset:17488
	ds_write_b32 v201, v104 offset:18016
	ds_write_b32 v201, v105 offset:18544
	ds_write_b32 v201, v84 offset:25408
	ds_write_b32 v201, v85 offset:25936
	ds_write_b32 v201, v86 offset:26464
	ds_write_b32 v201, v87 offset:26992
	s_addc_u32 s39, s41, 0
	s_waitcnt lgkmcnt(0)
	s_barrier
	v_lshl_add_u64 v[64:65], s[38:39], 0, v[98:99]
	v_lshl_add_u64 v[66:67], s[38:39], 0, v[134:135]
	v_lshl_add_u64 v[68:69], s[38:39], 0, v[136:137]
	v_lshl_add_u64 v[70:71], s[38:39], 0, v[138:139]
	global_load_dwordx2 v[178:179], v[64:65], off
	global_load_dwordx2 v[174:175], v[66:67], off
	global_load_dwordx2 v[170:171], v[68:69], off
	global_load_dwordx2 v[164:165], v[70:71], off
	v_lshl_add_u64 v[64:65], s[38:39], 0, v[140:141]
	v_lshl_add_u64 v[66:67], s[38:39], 0, v[142:143]
	v_lshl_add_u64 v[68:69], s[38:39], 0, v[144:145]
	v_lshl_add_u64 v[70:71], s[38:39], 0, v[146:147]
	global_load_dwordx2 v[176:177], v[64:65], off
	global_load_dwordx2 v[172:173], v[66:67], off
	global_load_dwordx2 v[168:169], v[68:69], off
	global_load_dwordx2 v[166:167], v[70:71], off
	s_add_u32 s30, s30, 0x8000
	s_addc_u32 s31, s31, 0
	s_cmp_gt_u32 s1, 61
	ds_read_b128 v[88:91], v200 offset:16384
	ds_read_b128 v[92:95], v200 offset:17408
	ds_read_b128 v[106:109], v200 offset:18432
	ds_read_b128 v[110:113], v200 offset:19456
	ds_read_b128 v[118:121], v200 offset:20480
	ds_read_b128 v[122:125], v200 offset:21504
	ds_read_b128 v[126:129], v200 offset:22528
	ds_read_b128 v[130:133], v200 offset:23552
	v_cvt_pk_bf16_f32 v64, v20, v21
	v_cvt_pk_bf16_f32 v65, v22, v23
	v_cvt_pk_bf16_f32 v66, v28, v29
	v_cvt_pk_bf16_f32 v67, v30, v31
	v_cvt_pk_bf16_f32 v68, v36, v37
	v_cvt_pk_bf16_f32 v69, v38, v39
	v_cvt_pk_bf16_f32 v70, v44, v45
	v_cvt_pk_bf16_f32 v71, v46, v47
	v_cvt_pk_bf16_f32 v72, v48, v49
	v_cvt_pk_bf16_f32 v73, v50, v51
	v_cvt_pk_bf16_f32 v74, v52, v53
	v_cvt_pk_bf16_f32 v75, v54, v55
	v_cvt_pk_bf16_f32 v76, v56, v57
	v_cvt_pk_bf16_f32 v77, v58, v59
	v_cvt_pk_bf16_f32 v78, v60, v61
	v_cvt_pk_bf16_f32 v79, v62, v63
	v_cvt_pk_bf16_f32 v84, v0, v1
	v_cvt_pk_bf16_f32 v85, v2, v3
	v_cvt_pk_bf16_f32 v86, v4, v5
	v_cvt_pk_bf16_f32 v87, v6, v7
	v_cvt_pk_bf16_f32 v80, v8, v9
	v_cvt_pk_bf16_f32 v81, v10, v11
	v_cvt_pk_bf16_f32 v82, v12, v13
	v_cvt_pk_bf16_f32 v83, v14, v15
	v_cvt_pk_bf16_f32 v102, v16, v17
	v_cvt_pk_bf16_f32 v103, v18, v19
	v_cvt_pk_bf16_f32 v104, v24, v25
	v_cvt_pk_bf16_f32 v105, v26, v27
	v_cvt_pk_bf16_f32 v114, v32, v33
	v_cvt_pk_bf16_f32 v115, v34, v35
	v_cvt_pk_bf16_f32 v116, v40, v41
	v_cvt_pk_bf16_f32 v117, v42, v43
	v_readlane_b32 s0, v96, s2
	s_waitcnt lgkmcnt(7)
	v_mfma_f32_16x16x32_bf16 v[204:207], v[88:91], v[64:67], 0
	v_mfma_f32_16x16x32_bf16 v[88:91], v[88:91], v[84:87], 0
	s_waitcnt lgkmcnt(6)
	v_mfma_f32_16x16x32_bf16 v[204:207], v[92:95], v[68:71], v[204:207]
	v_mfma_f32_16x16x32_bf16 v[88:91], v[92:95], v[80:83], v[88:91]
	s_waitcnt lgkmcnt(5)
	v_mfma_f32_16x16x32_bf16 v[92:95], v[106:109], v[72:75], v[204:207]
	v_mfma_f32_16x16x32_bf16 v[106:109], v[106:109], v[102:105], v[88:91]
	s_waitcnt lgkmcnt(4)
	v_mfma_f32_16x16x32_bf16 v[88:91], v[110:113], v[76:79], v[92:95]
	v_mfma_f32_16x16x32_bf16 v[92:95], v[110:113], v[114:117], v[106:109]
	s_nop 0
	ds_read_b128 v[204:207], v200 offset:24576
	ds_read_b128 v[208:211], v200 offset:25600
	ds_read_b128 v[212:215], v200 offset:26624
	ds_read_b128 v[216:219], v200 offset:27648
	s_waitcnt lgkmcnt(7)
	v_mfma_f32_16x16x32_bf16 v[106:109], v[118:121], v[64:67], 0
	v_mfma_f32_16x16x32_bf16 v[110:113], v[118:121], v[84:87], 0
	s_waitcnt lgkmcnt(6)
	v_mfma_f32_16x16x32_bf16 v[106:109], v[122:125], v[68:71], v[106:109]
	v_mfma_f32_16x16x32_bf16 v[110:113], v[122:125], v[80:83], v[110:113]
	s_waitcnt lgkmcnt(5)
	v_mfma_f32_16x16x32_bf16 v[106:109], v[126:129], v[72:75], v[106:109]
	v_mfma_f32_16x16x32_bf16 v[110:113], v[126:129], v[102:105], v[110:113]
	s_waitcnt lgkmcnt(4)
	v_mfma_f32_16x16x32_bf16 v[106:109], v[130:133], v[76:79], v[106:109]
	v_mfma_f32_16x16x32_bf16 v[110:113], v[130:133], v[114:117], v[110:113]
	ds_read_b128 v[126:129], v200 offset:28672
	ds_read_b128 v[130:133], v200 offset:29696
	ds_read_b128 v[220:223], v200 offset:30720
	ds_read_b128 v[234:237], v200 offset:31744
	s_waitcnt lgkmcnt(7)
	v_mfma_f32_16x16x32_bf16 v[118:121], v[204:207], v[64:67], 0
	v_mfma_f32_16x16x32_bf16 v[122:125], v[204:207], v[84:87], 0
	s_waitcnt lgkmcnt(6)
	v_mfma_f32_16x16x32_bf16 v[118:121], v[208:211], v[68:71], v[118:121]
	v_mfma_f32_16x16x32_bf16 v[122:125], v[208:211], v[80:83], v[122:125]
	s_waitcnt lgkmcnt(5)
	v_mfma_f32_16x16x32_bf16 v[118:121], v[212:215], v[72:75], v[118:121]
	v_mfma_f32_16x16x32_bf16 v[122:125], v[212:215], v[102:105], v[122:125]
	s_waitcnt lgkmcnt(4)
	v_mfma_f32_16x16x32_bf16 v[118:121], v[216:219], v[76:79], v[118:121]
	v_mfma_f32_16x16x32_bf16 v[122:125], v[216:219], v[114:117], v[122:125]
	ds_read_b128 v[204:207], v101 offset:57344
	ds_read_b128 v[208:211], v101 offset:58368
	ds_read_b128 v[212:215], v101 offset:59392
	ds_read_b128 v[216:219], v101 offset:60416
	s_waitcnt lgkmcnt(7)
	v_mfma_f32_16x16x32_bf16 v[238:241], v[126:129], v[64:67], 0
	v_mfma_f32_16x16x32_bf16 v[126:129], v[126:129], v[84:87], 0
	s_waitcnt lgkmcnt(6)
	v_mfma_f32_16x16x32_bf16 v[238:241], v[130:133], v[68:71], v[238:241]
	v_mfma_f32_16x16x32_bf16 v[126:129], v[130:133], v[80:83], v[126:129]
	s_waitcnt lgkmcnt(5)
	v_mfma_f32_16x16x32_bf16 v[130:133], v[220:223], v[72:75], v[238:241]
	v_mfma_f32_16x16x32_bf16 v[220:223], v[220:223], v[102:105], v[126:129]
	s_waitcnt lgkmcnt(4)
	v_mfma_f32_16x16x32_bf16 v[126:129], v[234:237], v[76:79], v[130:133]
	v_mfma_f32_16x16x32_bf16 v[130:133], v[234:237], v[114:117], v[220:223]
	s_nop 4
	ds_read_b128 v[220:223], v101 offset:61440
	ds_read_b128 v[234:237], v101 offset:62464
	ds_read_b128 v[238:241], v101 offset:63488
	ds_read_b128 v[242:245], v101 offset:64512
	s_waitcnt lgkmcnt(7)
	v_mfma_f32_16x16x32_bf16 v[246:249], v[204:207], v[64:67], 0
	s_waitcnt vmcnt(15)
	v_lshlrev_b32_e32 v182, 16, v198
	v_and_b32_e32 v183, 0xffff0000, v198
	v_lshlrev_b32_e32 v198, 16, v199
	v_mfma_f32_16x16x32_bf16 v[204:207], v[204:207], v[84:87], 0
	v_and_b32_e32 v199, 0xffff0000, v199
	s_waitcnt lgkmcnt(6)
	v_mfma_f32_16x16x32_bf16 v[246:249], v[208:211], v[68:71], v[246:249]
	v_mfma_f32_16x16x32_bf16 v[204:207], v[208:211], v[80:83], v[204:207]
	s_waitcnt lgkmcnt(5)
	v_mfma_f32_16x16x32_bf16 v[208:211], v[212:215], v[72:75], v[246:249]
	v_mfma_f32_16x16x32_bf16 v[204:207], v[212:215], v[102:105], v[204:207]
	s_waitcnt lgkmcnt(4)
	v_mfma_f32_16x16x32_bf16 v[208:211], v[216:219], v[76:79], v[208:211]
	v_mfma_f32_16x16x32_bf16 v[204:207], v[216:219], v[114:117], v[204:207]
	s_nop 6
	v_sub_f32_e32 v203, v199, v211
	v_sub_f32_e32 v224, v198, v210
	s_waitcnt vmcnt(11)
	v_lshlrev_b32_e32 v198, 16, v196
	v_and_b32_e32 v196, 0xffff0000, v196
	v_lshlrev_b32_e32 v199, 16, v197
	v_and_b32_e32 v197, 0xffff0000, v197
	v_sub_f32_e32 v183, v183, v209
	v_sub_f32_e32 v182, v182, v208
	v_sub_f32_e32 v225, v197, v207
	v_sub_f32_e32 v227, v199, v206
	v_sub_f32_e32 v233, v196, v205
	v_sub_f32_e32 v246, v198, v204
	ds_read_b128 v[196:199], v200 offset:8192
	ds_read_b128 v[204:207], v200 offset:9216
	ds_read_b128 v[208:211], v200 offset:10240
	ds_read_b128 v[212:215], v200 offset:11264
	s_waitcnt lgkmcnt(7)
	v_mfma_f32_16x16x32_bf16 v[216:219], v[220:223], v[64:67], 0
	v_mfma_f32_16x16x32_bf16 v[220:223], v[220:223], v[84:87], 0
	s_waitcnt lgkmcnt(6)
	v_mfma_f32_16x16x32_bf16 v[216:219], v[234:237], v[68:71], v[216:219]
	v_mfma_f32_16x16x32_bf16 v[220:223], v[234:237], v[80:83], v[220:223]
	v_lshlrev_b32_e32 v234, 16, v194
	v_and_b32_e32 v194, 0xffff0000, v194
	v_lshlrev_b32_e32 v235, 16, v195
	s_waitcnt lgkmcnt(5)
	v_mfma_f32_16x16x32_bf16 v[216:219], v[238:241], v[72:75], v[216:219]
	v_and_b32_e32 v195, 0xffff0000, v195
	v_mfma_f32_16x16x32_bf16 v[220:223], v[238:241], v[102:105], v[220:223]
	s_waitcnt lgkmcnt(4)
	v_mfma_f32_16x16x32_bf16 v[216:219], v[242:245], v[76:79], v[216:219]
	v_mfma_f32_16x16x32_bf16 v[220:223], v[242:245], v[114:117], v[220:223]
	s_nop 6
	v_sub_f32_e32 v242, v195, v219
	v_sub_f32_e32 v244, v194, v217
	s_waitcnt vmcnt(10)
	v_lshlrev_b32_e32 v194, 16, v192
	v_and_b32_e32 v192, 0xffff0000, v192
	v_lshlrev_b32_e32 v195, 16, v193
	v_and_b32_e32 v193, 0xffff0000, v193
	v_sub_f32_e32 v243, v235, v218
	v_sub_f32_e32 v245, v234, v216
	v_sub_f32_e32 v247, v193, v223
	v_sub_f32_e32 v248, v195, v222
	v_sub_f32_e32 v249, v192, v221
	v_sub_f32_e32 v250, v194, v220
	ds_read_b128 v[192:195], v200 offset:12288
	ds_read_b128 v[216:219], v200 offset:13312
	ds_read_b128 v[220:223], v200 offset:14336
	ds_read_b128 v[234:237], v200 offset:15360
	s_waitcnt lgkmcnt(7)
	v_mfma_f32_16x16x32_bf16 v[238:241], v[196:199], v[64:67], 0
	v_mfma_f32_16x16x32_bf16 v[196:199], v[196:199], v[84:87], 0
	s_waitcnt lgkmcnt(6)
	v_mfma_f32_16x16x32_bf16 v[238:241], v[204:207], v[68:71], v[238:241]
	v_mfma_f32_16x16x32_bf16 v[196:199], v[204:207], v[80:83], v[196:199]
	s_waitcnt lgkmcnt(5)
	v_mfma_f32_16x16x32_bf16 v[204:207], v[208:211], v[72:75], v[238:241]
	v_mfma_f32_16x16x32_bf16 v[196:199], v[208:211], v[102:105], v[196:199]
	v_lshlrev_b32_e32 v208, 16, v190
	v_and_b32_e32 v190, 0xffff0000, v190
	v_lshlrev_b32_e32 v209, 16, v191
	s_waitcnt lgkmcnt(4)
	v_mfma_f32_16x16x32_bf16 v[204:207], v[212:215], v[76:79], v[204:207]
	v_and_b32_e32 v191, 0xffff0000, v191
	v_mfma_f32_16x16x32_bf16 v[196:199], v[212:215], v[114:117], v[196:199]
	s_nop 5
	v_sub_f32_e32 v207, v191, v207
	v_sub_f32_e32 v205, v190, v205
	s_waitcnt vmcnt(9)
	v_lshlrev_b32_e32 v190, 16, v188
	v_and_b32_e32 v188, 0xffff0000, v188
	v_lshlrev_b32_e32 v191, 16, v189
	v_and_b32_e32 v189, 0xffff0000, v189
	v_sub_f32_e32 v206, v209, v206
	v_sub_f32_e32 v204, v208, v204
	v_sub_f32_e32 v208, v189, v199
	v_sub_f32_e32 v209, v191, v198
	v_sub_f32_e32 v210, v188, v197
	v_sub_f32_e32 v211, v190, v196
	ds_read_b128 v[188:191], v200 offset:49152
	ds_read_b128 v[196:199], v200 offset:50176
	s_waitcnt lgkmcnt(5)
	v_mfma_f32_16x16x32_bf16 v[64:67], v[192:195], v[64:67], 0
	s_waitcnt lgkmcnt(4)
	v_mfma_f32_16x16x32_bf16 v[64:67], v[216:219], v[68:71], v[64:67]
	v_lshlrev_b32_e32 v68, 16, v181
	v_and_b32_e32 v69, 0xffff0000, v181
	v_lshlrev_b32_e32 v70, 16, v180
	s_waitcnt lgkmcnt(3)
	v_mfma_f32_16x16x32_bf16 v[64:67], v[220:223], v[72:75], v[64:67]
	v_and_b32_e32 v71, 0xffff0000, v180
	s_waitcnt vmcnt(8)
	v_lshlrev_b32_e32 v74, 16, v186
	v_and_b32_e32 v75, 0xffff0000, v187
	v_mfma_f32_16x16x32_bf16 v[84:87], v[192:195], v[84:87], 0
	s_waitcnt lgkmcnt(2)
	v_mfma_f32_16x16x32_bf16 v[64:67], v[234:237], v[76:79], v[64:67]
	v_cvt_pk_bf16_f32 v76, v211, v210
	v_cvt_pk_bf16_f32 v77, v209, v208
	s_nop 5
	v_sub_f32_e32 v72, v69, v67
	v_sub_f32_e32 v73, v68, v66
	v_mfma_f32_16x16x32_bf16 v[66:69], v[216:219], v[80:83], v[84:87]
	v_sub_f32_e32 v71, v71, v65
	v_sub_f32_e32 v70, v70, v64
	v_cvt_pk_bf16_f32 v70, v70, v71
	v_mfma_f32_16x16x32_bf16 v[64:67], v[220:223], v[102:105], v[66:69]
	v_cvt_pk_bf16_f32 v71, v73, v72
	v_cvt_pk_bf16_f32 v72, v246, v233
	v_cvt_pk_bf16_f32 v73, v227, v225
	v_mfma_f32_16x16x32_bf16 v[64:67], v[234:237], v[114:117], v[64:67]
	v_and_b32_e32 v68, 0xffff0000, v186
	v_lshlrev_b32_e32 v69, 16, v187
	s_nop 5
	v_sub_f32_e32 v79, v75, v67
	v_sub_f32_e32 v80, v69, v66
	v_sub_f32_e32 v78, v68, v65
	v_sub_f32_e32 v81, v74, v64
	v_cvt_pk_bf16_f32 v64, v182, v183
	v_cvt_pk_bf16_f32 v65, v224, v203
	v_cvt_pk_bf16_f32 v66, v245, v244
	v_cvt_pk_bf16_f32 v67, v243, v242
	v_cvt_pk_bf16_f32 v68, v204, v205
	v_cvt_pk_bf16_f32 v69, v206, v207
	v_cvt_pk_bf16_f32 v74, v250, v249
	v_cvt_pk_bf16_f32 v75, v248, v247
	v_cvt_pk_bf16_f32 v78, v81, v78
	v_cvt_pk_bf16_f32 v79, v80, v79
	ds_read_b128 v[80:83], v200 offset:51200
	ds_read_b128 v[84:87], v200 offset:52224
	ds_read_b128 v[204:207], v200 offset:53248
	ds_read_b128 v[208:211], v200 offset:54272
	s_waitcnt lgkmcnt(5)
	v_mfma_f32_16x16x32_bf16 v[88:91], v[188:191], v[64:67], v[88:91]
	v_mfma_f32_16x16x32_bf16 v[92:95], v[188:191], v[72:75], v[92:95]
	s_waitcnt lgkmcnt(4)
	v_mfma_f32_16x16x32_bf16 v[88:91], v[196:199], v[68:71], v[88:91]
	v_mfma_f32_16x16x32_bf16 v[92:95], v[196:199], v[76:79], v[92:95]
	ds_read_b128 v[212:215], v200 offset:55296
	ds_read_b128 v[216:219], v200 offset:56320
	s_waitcnt lgkmcnt(5)
	v_mfma_f32_16x16x32_bf16 v[106:109], v[80:83], v[64:67], v[106:109]
	v_mfma_f32_16x16x32_bf16 v[80:83], v[80:83], v[72:75], v[110:113]
	s_waitcnt lgkmcnt(4)
	v_mfma_f32_16x16x32_bf16 v[106:109], v[84:87], v[68:71], v[106:109]
	v_mfma_f32_16x16x32_bf16 v[80:83], v[84:87], v[76:79], v[80:83]
	ds_read_b128 v[220:223], v200 offset:32768
	ds_read_b128 v[234:237], v200 offset:33792
	s_waitcnt lgkmcnt(5)
	v_mfma_f32_16x16x32_bf16 v[118:121], v[204:207], v[64:67], v[118:121]
	v_mfma_f32_16x16x32_bf16 v[102:105], v[204:207], v[72:75], v[122:125]
	s_waitcnt lgkmcnt(4)
	v_mfma_f32_16x16x32_bf16 v[118:121], v[208:211], v[68:71], v[118:121]
	v_mfma_f32_16x16x32_bf16 v[102:105], v[208:211], v[76:79], v[102:105]
	ds_read_b128 v[204:207], v200 offset:34816
	ds_read_b128 v[208:211], v200 offset:35840
	s_waitcnt lgkmcnt(5)
	v_mfma_f32_16x16x32_bf16 v[126:129], v[212:215], v[64:67], v[126:129]
	v_mfma_f32_16x16x32_bf16 v[84:87], v[212:215], v[72:75], v[130:133]
	s_waitcnt lgkmcnt(4)
	v_mfma_f32_16x16x32_bf16 v[126:129], v[216:219], v[68:71], v[126:129]
	v_mfma_f32_16x16x32_bf16 v[84:87], v[216:219], v[76:79], v[84:87]
	ds_read_b128 v[212:215], v200 offset:36864
	ds_read_b128 v[216:219], v200 offset:37888
	v_pk_mul_f32 v[22:23], v[22:23], s[0:1] op_sel_hi:[1,0]
	v_pk_mul_f32 v[20:21], v[20:21], s[0:1] op_sel_hi:[1,0]
	v_pk_mul_f32 v[2:3], v[2:3], s[0:1] op_sel_hi:[1,0]
	v_pk_mul_f32 v[0:1], v[0:1], s[0:1] op_sel_hi:[1,0]
	s_waitcnt lgkmcnt(5)
	v_mfma_f32_16x16x32_bf16 v[20:23], v[220:223], v[64:67], v[20:23]
	v_mfma_f32_16x16x32_bf16 v[114:117], v[220:223], v[72:75], v[0:3]
	s_waitcnt lgkmcnt(4)
	v_mfma_f32_16x16x32_bf16 v[0:3], v[234:237], v[68:71], v[20:23]
	v_mfma_f32_16x16x32_bf16 v[20:23], v[234:237], v[76:79], v[114:117]
	ds_read_b128 v[220:223], v200 offset:38912
	ds_read_b128 v[234:237], v200 offset:39936
	v_pk_mul_f32 v[30:31], v[30:31], s[0:1] op_sel_hi:[1,0]
	v_pk_mul_f32 v[28:29], v[28:29], s[0:1] op_sel_hi:[1,0]
	v_pk_mul_f32 v[6:7], v[6:7], s[0:1] op_sel_hi:[1,0]
	v_pk_mul_f32 v[4:5], v[4:5], s[0:1] op_sel_hi:[1,0]
	s_waitcnt lgkmcnt(5)
	v_mfma_f32_16x16x32_bf16 v[28:31], v[204:207], v[64:67], v[28:31]
	v_mfma_f32_16x16x32_bf16 v[110:113], v[204:207], v[72:75], v[4:7]
	s_waitcnt lgkmcnt(4)
	v_mfma_f32_16x16x32_bf16 v[4:7], v[208:211], v[68:71], v[28:31]
	v_mfma_f32_16x16x32_bf16 v[28:31], v[208:211], v[76:79], v[110:113]
	ds_read_b128 v[204:207], v200 offset:40960
	ds_read_b128 v[208:211], v200 offset:41984
	v_pk_mul_f32 v[38:39], v[38:39], s[0:1] op_sel_hi:[1,0]
	v_pk_mul_f32 v[36:37], v[36:37], s[0:1] op_sel_hi:[1,0]
	v_pk_mul_f32 v[10:11], v[10:11], s[0:1] op_sel_hi:[1,0]
	v_pk_mul_f32 v[8:9], v[8:9], s[0:1] op_sel_hi:[1,0]
	s_waitcnt lgkmcnt(5)
	v_mfma_f32_16x16x32_bf16 v[36:39], v[212:215], v[64:67], v[36:39]
	v_mfma_f32_16x16x32_bf16 v[114:117], v[212:215], v[72:75], v[8:11]
	s_waitcnt lgkmcnt(4)
	v_mfma_f32_16x16x32_bf16 v[8:11], v[216:219], v[68:71], v[36:39]
	v_mfma_f32_16x16x32_bf16 v[36:39], v[216:219], v[76:79], v[114:117]
	ds_read_b128 v[212:215], v200 offset:43008
	ds_read_b128 v[216:219], v200 offset:44032
	v_pk_mul_f32 v[46:47], v[46:47], s[0:1] op_sel_hi:[1,0]
	v_pk_mul_f32 v[44:45], v[44:45], s[0:1] op_sel_hi:[1,0]
	v_pk_mul_f32 v[14:15], v[14:15], s[0:1] op_sel_hi:[1,0]
	v_pk_mul_f32 v[12:13], v[12:13], s[0:1] op_sel_hi:[1,0]
	s_waitcnt lgkmcnt(5)
	v_mfma_f32_16x16x32_bf16 v[44:47], v[220:223], v[64:67], v[44:47]
	v_mfma_f32_16x16x32_bf16 v[110:113], v[220:223], v[72:75], v[12:15]
	s_waitcnt lgkmcnt(4)
	v_mfma_f32_16x16x32_bf16 v[12:15], v[234:237], v[68:71], v[44:47]
	v_mfma_f32_16x16x32_bf16 v[44:47], v[234:237], v[76:79], v[110:113]
	ds_read_b128 v[220:223], v200 offset:45056
	ds_read_b128 v[234:237], v200 offset:46080
	v_pk_mul_f32 v[50:51], v[50:51], s[0:1] op_sel_hi:[1,0]
	v_pk_mul_f32 v[48:49], v[48:49], s[0:1] op_sel_hi:[1,0]
	v_pk_mul_f32 v[18:19], v[18:19], s[0:1] op_sel_hi:[1,0]
	v_pk_mul_f32 v[16:17], v[16:17], s[0:1] op_sel_hi:[1,0]
	s_waitcnt lgkmcnt(5)
	v_mfma_f32_16x16x32_bf16 v[48:51], v[204:207], v[64:67], v[48:51]
	v_mfma_f32_16x16x32_bf16 v[114:117], v[204:207], v[72:75], v[16:19]
	s_waitcnt lgkmcnt(4)
	v_mfma_f32_16x16x32_bf16 v[16:19], v[208:211], v[68:71], v[48:51]
	v_mfma_f32_16x16x32_bf16 v[48:51], v[208:211], v[76:79], v[114:117]
	ds_read_b128 v[204:207], v200 offset:47104
	ds_read_b128 v[208:211], v200 offset:48128
	v_pk_mul_f32 v[54:55], v[54:55], s[0:1] op_sel_hi:[1,0]
	v_pk_mul_f32 v[52:53], v[52:53], s[0:1] op_sel_hi:[1,0]
	v_pk_mul_f32 v[26:27], v[26:27], s[0:1] op_sel_hi:[1,0]
	v_pk_mul_f32 v[24:25], v[24:25], s[0:1] op_sel_hi:[1,0]
	s_waitcnt lgkmcnt(5)
	v_mfma_f32_16x16x32_bf16 v[52:55], v[212:215], v[64:67], v[52:55]
	v_mfma_f32_16x16x32_bf16 v[110:113], v[212:215], v[72:75], v[24:27]
	s_waitcnt lgkmcnt(4)
	v_mfma_f32_16x16x32_bf16 v[24:27], v[216:219], v[68:71], v[52:55]
	v_mfma_f32_16x16x32_bf16 v[52:55], v[216:219], v[76:79], v[110:113]
	v_pk_mul_f32 v[58:59], v[58:59], s[0:1] op_sel_hi:[1,0]
	v_pk_mul_f32 v[56:57], v[56:57], s[0:1] op_sel_hi:[1,0]
	v_pk_mul_f32 v[34:35], v[34:35], s[0:1] op_sel_hi:[1,0]
	v_pk_mul_f32 v[32:33], v[32:33], s[0:1] op_sel_hi:[1,0]
	s_waitcnt lgkmcnt(3)
	v_mfma_f32_16x16x32_bf16 v[56:59], v[220:223], v[64:67], v[56:59]
	v_mfma_f32_16x16x32_bf16 v[114:117], v[220:223], v[72:75], v[32:35]
	s_waitcnt lgkmcnt(2)
	v_mfma_f32_16x16x32_bf16 v[32:35], v[234:237], v[68:71], v[56:59]
	v_mfma_f32_16x16x32_bf16 v[56:59], v[234:237], v[76:79], v[114:117]
	v_mul_f32_e64 v62, v62, s0
	v_mul_f32_e64 v63, v63, s0
	v_pk_mul_f32 v[60:61], v[60:61], s[0:1] op_sel_hi:[1,0]
	v_pk_mul_f32 v[42:43], v[42:43], s[0:1] op_sel_hi:[1,0]
	v_pk_mul_f32 v[40:41], v[40:41], s[0:1] op_sel_hi:[1,0]
	s_waitcnt lgkmcnt(1)
	v_mfma_f32_16x16x32_bf16 v[60:63], v[204:207], v[64:67], v[60:63]
	v_mfma_f32_16x16x32_bf16 v[64:67], v[204:207], v[72:75], v[40:43]
	s_waitcnt lgkmcnt(0)
	v_mfma_f32_16x16x32_bf16 v[40:43], v[208:211], v[68:71], v[60:63]
	v_mfma_f32_16x16x32_bf16 v[60:63], v[208:211], v[76:79], v[64:67]
	s_waitcnt lgkmcnt(0)
	s_barrier
	ds_write_b32 v201, v88
	ds_write_b32 v201, v89 offset:528
	ds_write_b32 v201, v90 offset:1056
	ds_write_b32 v202, v91
	ds_write_b32 v201, v106 offset:8448
	ds_write_b32 v201, v107 offset:8976
	ds_write_b32 v201, v108 offset:9504
	ds_write_b32 v201, v109 offset:10032
	ds_write_b32 v201, v118 offset:16896
	ds_write_b32 v201, v119 offset:17424
	ds_write_b32 v201, v120 offset:17952
	ds_write_b32 v201, v121 offset:18480
	ds_write_b32 v201, v126 offset:25344
	ds_write_b32 v201, v127 offset:25872
	ds_write_b32 v201, v128 offset:26400
	ds_write_b32 v201, v129 offset:26928
	ds_write_b32 v201, v92 offset:64
	ds_write_b32 v201, v93 offset:592
	ds_write_b32 v201, v94 offset:1120
	ds_write_b32 v202, v95 offset:64
	ds_write_b32 v201, v80 offset:8512
	ds_write_b32 v201, v81 offset:9040
	ds_write_b32 v201, v82 offset:9568
	ds_write_b32 v201, v83 offset:10096
	ds_write_b32 v201, v102 offset:16960
	ds_write_b32 v201, v103 offset:17488
	ds_write_b32 v201, v104 offset:18016
	ds_write_b32 v201, v105 offset:18544
	ds_write_b32 v201, v84 offset:25408
	ds_write_b32 v201, v85 offset:25936
	ds_write_b32 v201, v86 offset:26464
	ds_write_b32 v201, v87 offset:26992
	s_waitcnt lgkmcnt(0)
	s_barrier
	s_mov_b32 s1, s36
	s_cbranch_scc0 .LBB0_988
	s_waitcnt lgkmcnt(0)
	s_barrier
	s_waitcnt lgkmcnt(0)
	s_barrier
	v_mov_b32_e32 v227, 1
	v_mov_b64_e32 v[244:245], 0x100
